# P + last K-loop trip skips the shared closing barrier (leading half no longer idles one MFMA interval before its epilogue; barrier counts stay paired)
# baseline (speedup 1.0000x reference)
; #define PG8_STAGE(bufoff, gbase, voff) do { _Pragma("unroll") for (int _i = 0; _i < 2; ++_i) \
;         __builtin_amdgcn_global_load_lds((const unsigned*)((const char*)(gbase) + (voff)[_i]), (PG8_LAS unsigned*)(lds + (bufoff) + ldsw + _i * 8192), 16, 0, 0); } while (0)
; #define PG8_LDA(dst, b, h) do { _Pragma("unroll") for (int m = 0; m < 4; ++m) _Pragma("unroll") for (int k = 0; k < 2; ++k) dst[m][k] = *(const PG8_LAS bf16x8*)(lds + PG8_SA(b, h) + aoff + m * 2048 + k * 1024); } while (0)
; #define PG8_LDB(dst, b, h) do { _Pragma("unroll") for (int n = 0; n < 2; ++n) _Pragma("unroll") for (int k = 0; k < 2; ++k) dst[n][k] = *(const PG8_LAS bf16x8*)(lds + PG8_SB(b, h) + boff + n * 2048 + k * 1024); } while (0)
; #define PG8_MMA(ai, bj, At, Bt) do { __builtin_amdgcn_s_setprio(1); _Pragma("unroll") for (int m = 0; m < 4; ++m) _Pragma("unroll") for (int n = 0; n < 2; ++n) _Pragma("unroll") for (int k = 0; k < 2; ++k) \
;         acc[ai][bj][m][n] = __builtin_amdgcn_mfma_f32_16x16x32_bf16(Bt[n][k], At[m][k], acc[ai][bj][m][n], 0, 0, 0); __builtin_amdgcn_s_setprio(0); } while (0)
; #define PG8_WAIT_V(n) asm volatile("s_waitcnt vmcnt(" #n ")" ::: "memory")
; #define PG8_WAIT_L(n) asm volatile("s_waitcnt lgkmcnt(" #n ")" ::: "memory")
; #define PG8_BAR __builtin_amdgcn_s_barrier()
; #define PG8_SCHED __builtin_amdgcn_sched_barrier(0)
; template <class Epi, class Sched, bool ALIGN_EPI = false, bool SP2 = false>
; __device__ __forceinline__ void gemm_phase(PG8_LAS unsigned char* lds, const Gemm g, const Sched& S, const Epi& E) {
;     ...
;             PG8_LDB(B0, 0, 0); PG8_LDB(B1, 0, 1); PG8_SCHED; PG8_LDA(At, 0, 0); PG8_STAGE(PG8_SA(1, 1), a1 + hstep, voffA);
;             PG8_WAIT_V(8); PG8_WAIT_L(0); PG8_BAR; PG8_MMA(0, 0, At, B0); PG8_MMA(0, 1, At, B1); PG8_BAR; PG8_SCHED;
;             PG8_LDA(At, 0, 1); PG8_STAGE(PG8_SB(0, 0), b2, voffB); PG8_STAGE(PG8_SB(0, 1), b2 + hstep, voffB); PG8_STAGE(PG8_SA(0, 0), a2, voffA);
;             PG8_WAIT_V(8); PG8_WAIT_L(0); PG8_BAR; PG8_MMA(1, 0, At, B0); PG8_MMA(1, 1, At, B1); PG8_BAR; PG8_SCHED;
.LBB0_165:
	s_add_u32 s68, s42, 0xfff80080
	s_addc_u32 s69, s43, -1
	s_add_i32 s82, 0, 0x10000
	s_cmp_eq_u32 s71, 28
	s_cselect_b32 s81, s47, s69
	s_cselect_b32 s80, s55, s68
	v_add_u32_e32 v144, s82, v147
	s_cselect_b32 s79, s45, s63
	s_cselect_b32 s78, s58, s59
	s_add_i32 s83, 0, 0x14000
	ds_read_b128 v[140:143], v144
	ds_read_b128 v[156:159], v144 offset:1024
	ds_read_b128 v[160:163], v144 offset:2048
	ds_read_b128 v[164:167], v144 offset:3072
	v_add_u32_e32 v144, s83, v147
	ds_read_b128 v[168:171], v144
	ds_read_b128 v[172:175], v144 offset:1024
	ds_read_b128 v[192:195], v144 offset:2048
	ds_read_b128 v[196:199], v144 offset:3072
	v_lshl_add_u64 v[150:151], s[42:43], 0, v[136:137]
	s_add_i32 m0, s14, 0xc000
	ds_read_b128 v[200:203], v149
	ds_read_b128 v[204:207], v149 offset:1024
	ds_read_b128 v[208:211], v149 offset:2048
	ds_read_b128 v[212:215], v149 offset:3072
	ds_read_b128 v[216:219], v149 offset:4096
	ds_read_b128 v[220:223], v149 offset:5120
	ds_read_b128 v[224:227], v149 offset:6144
	ds_read_b128 v[228:231], v149 offset:7168
	global_load_lds_dwordx4 v[150:151], off
	v_lshl_add_u64 v[150:151], s[42:43], 0, v[138:139]
	s_add_i32 m0, s14, 0xe000
	s_nop 0
	global_load_lds_dwordx4 v[150:151], off
	s_waitcnt vmcnt(8)
	s_waitcnt lgkmcnt(0)
	s_setprio 1
	s_barrier
	v_mfma_f32_16x16x32_bf16 v[124:127], v[140:143], v[200:203], v[124:127]
	v_mfma_f32_16x16x32_bf16 v[120:123], v[160:163], v[200:203], v[120:123]
	v_mfma_f32_16x16x32_bf16 v[108:111], v[140:143], v[208:211], v[108:111]
	v_mfma_f32_16x16x32_bf16 v[104:107], v[160:163], v[208:211], v[104:107]
	v_mfma_f32_16x16x32_bf16 v[92:95], v[140:143], v[216:219], v[92:95]
	v_mfma_f32_16x16x32_bf16 v[88:91], v[160:163], v[216:219], v[88:91]
	v_mfma_f32_16x16x32_bf16 v[76:79], v[140:143], v[224:227], v[76:79]
	v_mfma_f32_16x16x32_bf16 v[72:75], v[160:163], v[224:227], v[72:75]
	v_mfma_f32_16x16x32_bf16 v[124:127], v[156:159], v[204:207], v[124:127]
	v_mfma_f32_16x16x32_bf16 v[120:123], v[164:167], v[204:207], v[120:123]
	v_mfma_f32_16x16x32_bf16 v[108:111], v[156:159], v[212:215], v[108:111]
	v_mfma_f32_16x16x32_bf16 v[104:107], v[164:167], v[212:215], v[104:107]
	v_mfma_f32_16x16x32_bf16 v[92:95], v[156:159], v[220:223], v[92:95]
	v_mfma_f32_16x16x32_bf16 v[88:91], v[164:167], v[220:223], v[88:91]
	v_mfma_f32_16x16x32_bf16 v[76:79], v[156:159], v[228:231], v[76:79]
	v_mfma_f32_16x16x32_bf16 v[72:75], v[164:167], v[228:231], v[72:75]
	v_mfma_f32_16x16x32_bf16 v[116:119], v[168:171], v[200:203], v[116:119]
	v_mfma_f32_16x16x32_bf16 v[112:115], v[192:195], v[200:203], v[112:115]
	v_mfma_f32_16x16x32_bf16 v[100:103], v[168:171], v[208:211], v[100:103]
	v_mfma_f32_16x16x32_bf16 v[96:99], v[192:195], v[208:211], v[96:99]
	v_mfma_f32_16x16x32_bf16 v[84:87], v[168:171], v[216:219], v[84:87]
	v_mfma_f32_16x16x32_bf16 v[80:83], v[192:195], v[216:219], v[80:83]
	v_mfma_f32_16x16x32_bf16 v[68:71], v[168:171], v[224:227], v[68:71]
	v_mfma_f32_16x16x32_bf16 v[64:67], v[192:195], v[224:227], v[64:67]
	v_mfma_f32_16x16x32_bf16 v[116:119], v[172:175], v[204:207], v[116:119]
	v_mfma_f32_16x16x32_bf16 v[112:115], v[196:199], v[204:207], v[112:115]
	v_mfma_f32_16x16x32_bf16 v[100:103], v[172:175], v[212:215], v[100:103]
	v_mfma_f32_16x16x32_bf16 v[96:99], v[196:199], v[212:215], v[96:99]
	v_mfma_f32_16x16x32_bf16 v[84:87], v[172:175], v[220:223], v[84:87]
	v_mfma_f32_16x16x32_bf16 v[80:83], v[196:199], v[220:223], v[80:83]
	v_mfma_f32_16x16x32_bf16 v[68:71], v[172:175], v[228:231], v[68:71]
	v_mfma_f32_16x16x32_bf16 v[64:67], v[196:199], v[228:231], v[64:67]
	s_barrier
	s_setprio 0
	s_add_i32 s68, s82, s0
	v_lshl_add_u64 v[150:151], s[78:79], 0, v[152:153]
	s_mov_b32 m0, s68
	ds_read_b128 v[200:203], v149 offset:16384
	ds_read_b128 v[204:207], v149 offset:17408
	ds_read_b128 v[208:211], v149 offset:18432
	ds_read_b128 v[212:215], v149 offset:19456
	ds_read_b128 v[216:219], v149 offset:20480
	ds_read_b128 v[220:223], v149 offset:21504
	ds_read_b128 v[224:227], v149 offset:22528
	ds_read_b128 v[228:231], v149 offset:23552
	global_load_lds_dwordx4 v[150:151], off
	s_add_i32 m0, s68, 0x2000
	s_add_u32 s68, s78, 0x80000
	v_lshl_add_u64 v[182:183], s[78:79], 0, v[128:129]
	s_addc_u32 s69, s79, 0
	s_add_i32 s82, s83, s0
	global_load_lds_dwordx4 v[182:183], off
	v_lshl_add_u64 v[184:185], s[68:69], 0, v[152:153]
	s_mov_b32 m0, s82
	v_lshl_add_u64 v[188:189], s[80:81], 0, v[130:131]
	global_load_lds_dwordx4 v[184:185], off
	v_lshl_add_u64 v[184:185], s[68:69], 0, v[128:129]
	s_add_i32 m0, s82, 0x2000
	s_nop 0
	global_load_lds_dwordx4 v[184:185], off
	v_lshl_add_u64 v[184:185], s[80:81], 0, v[132:133]
	s_mov_b32 m0, s14
	s_nop 0
	global_load_lds_dwordx4 v[184:185], off
	s_mov_b32 m0, s15
	s_nop 0
	global_load_lds_dwordx4 v[188:189], off
	s_waitcnt vmcnt(8)
	s_waitcnt lgkmcnt(0)
	s_setprio 1
	s_barrier
; #define PG8_STAGE(bufoff, gbase, voff) do { _Pragma("unroll") for (int _i = 0; _i < 2; ++_i) \
;         __builtin_amdgcn_global_load_lds((const unsigned*)((const char*)(gbase) + (voff)[_i]), (PG8_LAS unsigned*)(lds + (bufoff) + ldsw + _i * 8192), 16, 0, 0); } while (0)
; #define PG8_LDA(dst, b, h) do { _Pragma("unroll") for (int m = 0; m < 4; ++m) _Pragma("unroll") for (int k = 0; k < 2; ++k) dst[m][k] = *(const PG8_LAS bf16x8*)(lds + PG8_SA(b, h) + aoff + m * 2048 + k * 1024); } while (0)
; #define PG8_LDB(dst, b, h) do { _Pragma("unroll") for (int n = 0; n < 2; ++n) _Pragma("unroll") for (int k = 0; k < 2; ++k) dst[n][k] = *(const PG8_LAS bf16x8*)(lds + PG8_SB(b, h) + boff + n * 2048 + k * 1024); } while (0)
; #define PG8_MMA(ai, bj, At, Bt) do { __builtin_amdgcn_s_setprio(1); _Pragma("unroll") for (int m = 0; m < 4; ++m) _Pragma("unroll") for (int n = 0; n < 2; ++n) _Pragma("unroll") for (int k = 0; k < 2; ++k) \
;         acc[ai][bj][m][n] = __builtin_amdgcn_mfma_f32_16x16x32_bf16(Bt[n][k], At[m][k], acc[ai][bj][m][n], 0, 0, 0); __builtin_amdgcn_s_setprio(0); } while (0)
; #define PG8_WAIT_V(n) asm volatile("s_waitcnt vmcnt(" #n ")" ::: "memory")
; #define PG8_WAIT_L(n) asm volatile("s_waitcnt lgkmcnt(" #n ")" ::: "memory")
; #define PG8_BAR __builtin_amdgcn_s_barrier()
; #define PG8_SCHED __builtin_amdgcn_sched_barrier(0)
; template <class Epi, class Sched, bool ALIGN_EPI = false, bool SP2 = false>
; __device__ __forceinline__ void gemm_phase(PG8_LAS unsigned char* lds, const Gemm g, const Sched& S, const Epi& E) {
;     ...
;             PG8_WAIT_V(8); PG8_WAIT_L(0); PG8_BAR; PG8_MMA(1, 0, At, B0); PG8_MMA(1, 1, At, B1); PG8_BAR; PG8_SCHED;
;             PG8_LDB(B0, 1, 0); PG8_LDB(B1, 1, 1); PG8_SCHED; PG8_LDA(At, 1, 0); PG8_STAGE(PG8_SA(0, 1), a2 + hstep, voffA);
;             PG8_WAIT_V(8); PG8_WAIT_L(0); PG8_BAR; PG8_MMA(0, 0, At, B0); PG8_MMA(0, 1, At, B1); PG8_BAR; PG8_SCHED;
;             PG8_LDA(At, 1, 1); PG8_STAGE(PG8_SB(1, 0), b3, voffB); PG8_STAGE(PG8_SB(1, 1), b3 + hstep, voffB); PG8_STAGE(PG8_SA(1, 0), a3, voffA);
	v_mfma_f32_16x16x32_bf16 v[60:63], v[140:143], v[200:203], v[60:63]
	v_mfma_f32_16x16x32_bf16 v[56:59], v[160:163], v[200:203], v[56:59]
	v_mfma_f32_16x16x32_bf16 v[44:47], v[140:143], v[208:211], v[44:47]
	v_mfma_f32_16x16x32_bf16 v[40:43], v[160:163], v[208:211], v[40:43]
	v_mfma_f32_16x16x32_bf16 v[28:31], v[140:143], v[216:219], v[28:31]
	v_mfma_f32_16x16x32_bf16 v[24:27], v[160:163], v[216:219], v[24:27]
	v_mfma_f32_16x16x32_bf16 v[12:15], v[140:143], v[224:227], v[12:15]
	v_mfma_f32_16x16x32_bf16 v[8:11], v[160:163], v[224:227], v[8:11]
	v_mfma_f32_16x16x32_bf16 v[60:63], v[156:159], v[204:207], v[60:63]
	v_mfma_f32_16x16x32_bf16 v[56:59], v[164:167], v[204:207], v[56:59]
	v_mfma_f32_16x16x32_bf16 v[44:47], v[156:159], v[212:215], v[44:47]
	v_mfma_f32_16x16x32_bf16 v[40:43], v[164:167], v[212:215], v[40:43]
	v_mfma_f32_16x16x32_bf16 v[28:31], v[156:159], v[220:223], v[28:31]
	v_mfma_f32_16x16x32_bf16 v[24:27], v[164:167], v[220:223], v[24:27]
	v_mfma_f32_16x16x32_bf16 v[12:15], v[156:159], v[228:231], v[12:15]
	v_mfma_f32_16x16x32_bf16 v[8:11], v[164:167], v[228:231], v[8:11]
	v_mfma_f32_16x16x32_bf16 v[52:55], v[168:171], v[200:203], v[52:55]
	v_mfma_f32_16x16x32_bf16 v[48:51], v[192:195], v[200:203], v[48:51]
	v_mfma_f32_16x16x32_bf16 v[36:39], v[168:171], v[208:211], v[36:39]
	v_mfma_f32_16x16x32_bf16 v[32:35], v[192:195], v[208:211], v[32:35]
	v_mfma_f32_16x16x32_bf16 v[20:23], v[168:171], v[216:219], v[20:23]
	v_mfma_f32_16x16x32_bf16 v[16:19], v[192:195], v[216:219], v[16:19]
	v_mfma_f32_16x16x32_bf16 v[4:7], v[168:171], v[224:227], v[4:7]
	v_mfma_f32_16x16x32_bf16 v[0:3], v[192:195], v[224:227], v[0:3]
	v_mfma_f32_16x16x32_bf16 v[52:55], v[172:175], v[204:207], v[52:55]
	v_mfma_f32_16x16x32_bf16 v[48:51], v[196:199], v[204:207], v[48:51]
	v_mfma_f32_16x16x32_bf16 v[36:39], v[172:175], v[212:215], v[36:39]
	v_mfma_f32_16x16x32_bf16 v[32:35], v[196:199], v[212:215], v[32:35]
	v_mfma_f32_16x16x32_bf16 v[20:23], v[172:175], v[220:223], v[20:23]
	v_mfma_f32_16x16x32_bf16 v[16:19], v[196:199], v[220:223], v[16:19]
	v_mfma_f32_16x16x32_bf16 v[4:7], v[172:175], v[228:231], v[4:7]
	v_mfma_f32_16x16x32_bf16 v[0:3], v[196:199], v[228:231], v[0:3]
	s_barrier
	s_setprio 0
	v_add_u32_e32 v144, s93, v147
	s_add_i32 s82, 0, 0x1c000
	ds_read_b128 v[140:143], v144
	ds_read_b128 v[156:159], v144 offset:1024
	ds_read_b128 v[160:163], v144 offset:2048
	ds_read_b128 v[164:167], v144 offset:3072
	v_add_u32_e32 v144, s82, v147
	ds_read_b128 v[168:171], v144
	ds_read_b128 v[172:175], v144 offset:1024
	ds_read_b128 v[192:195], v144 offset:2048
	ds_read_b128 v[196:199], v144 offset:3072
	s_add_u32 s68, s80, 0x80000
	s_addc_u32 s69, s81, 0
	s_mov_b32 m0, s16
	v_lshl_add_u64 v[190:191], s[68:69], 0, v[132:133]
	ds_read_b128 v[200:203], v149 offset:32768
	ds_read_b128 v[204:207], v149 offset:33792
	ds_read_b128 v[208:211], v149 offset:34816
	ds_read_b128 v[212:215], v149 offset:35840
	ds_read_b128 v[216:219], v149 offset:36864
	ds_read_b128 v[220:223], v149 offset:37888
	ds_read_b128 v[224:227], v149 offset:38912
	ds_read_b128 v[228:231], v149 offset:39936
	global_load_lds_dwordx4 v[190:191], off
	v_lshl_add_u64 v[190:191], s[68:69], 0, v[130:131]
	s_mov_b32 m0, s17
	s_nop 0
	global_load_lds_dwordx4 v[190:191], off
	s_waitcnt vmcnt(8)
	s_waitcnt lgkmcnt(0)
	s_setprio 1
	s_barrier
	v_mfma_f32_16x16x32_bf16 v[124:127], v[140:143], v[200:203], v[124:127]
	v_mfma_f32_16x16x32_bf16 v[120:123], v[160:163], v[200:203], v[120:123]
	v_mfma_f32_16x16x32_bf16 v[108:111], v[140:143], v[208:211], v[108:111]
	v_mfma_f32_16x16x32_bf16 v[104:107], v[160:163], v[208:211], v[104:107]
	v_mfma_f32_16x16x32_bf16 v[92:95], v[140:143], v[216:219], v[92:95]
	v_mfma_f32_16x16x32_bf16 v[88:91], v[160:163], v[216:219], v[88:91]
	v_mfma_f32_16x16x32_bf16 v[76:79], v[140:143], v[224:227], v[76:79]
	v_mfma_f32_16x16x32_bf16 v[72:75], v[160:163], v[224:227], v[72:75]
	v_mfma_f32_16x16x32_bf16 v[124:127], v[156:159], v[204:207], v[124:127]
	v_mfma_f32_16x16x32_bf16 v[120:123], v[164:167], v[204:207], v[120:123]
	v_mfma_f32_16x16x32_bf16 v[108:111], v[156:159], v[212:215], v[108:111]
	v_mfma_f32_16x16x32_bf16 v[104:107], v[164:167], v[212:215], v[104:107]
	v_mfma_f32_16x16x32_bf16 v[92:95], v[156:159], v[220:223], v[92:95]
	v_mfma_f32_16x16x32_bf16 v[88:91], v[164:167], v[220:223], v[88:91]
	v_mfma_f32_16x16x32_bf16 v[76:79], v[156:159], v[228:231], v[76:79]
	v_mfma_f32_16x16x32_bf16 v[72:75], v[164:167], v[228:231], v[72:75]
	v_mfma_f32_16x16x32_bf16 v[116:119], v[168:171], v[200:203], v[116:119]
	v_mfma_f32_16x16x32_bf16 v[112:115], v[192:195], v[200:203], v[112:115]
	v_mfma_f32_16x16x32_bf16 v[100:103], v[168:171], v[208:211], v[100:103]
	v_mfma_f32_16x16x32_bf16 v[96:99], v[192:195], v[208:211], v[96:99]
	v_mfma_f32_16x16x32_bf16 v[84:87], v[168:171], v[216:219], v[84:87]
	v_mfma_f32_16x16x32_bf16 v[80:83], v[192:195], v[216:219], v[80:83]
	v_mfma_f32_16x16x32_bf16 v[68:71], v[168:171], v[224:227], v[68:71]
	v_mfma_f32_16x16x32_bf16 v[64:67], v[192:195], v[224:227], v[64:67]
	v_mfma_f32_16x16x32_bf16 v[116:119], v[172:175], v[204:207], v[116:119]
	v_mfma_f32_16x16x32_bf16 v[112:115], v[196:199], v[204:207], v[112:115]
	v_mfma_f32_16x16x32_bf16 v[100:103], v[172:175], v[212:215], v[100:103]
	v_mfma_f32_16x16x32_bf16 v[96:99], v[196:199], v[212:215], v[96:99]
	v_mfma_f32_16x16x32_bf16 v[84:87], v[172:175], v[220:223], v[84:87]
	v_mfma_f32_16x16x32_bf16 v[80:83], v[196:199], v[220:223], v[80:83]
	v_mfma_f32_16x16x32_bf16 v[68:71], v[172:175], v[228:231], v[68:71]
	v_mfma_f32_16x16x32_bf16 v[64:67], v[196:199], v[228:231], v[64:67]
	s_barrier
; #define PG8_STAGE(bufoff, gbase, voff) do { _Pragma("unroll") for (int _i = 0; _i < 2; ++_i) \
;         __builtin_amdgcn_global_load_lds((const unsigned*)((const char*)(gbase) + (voff)[_i]), (PG8_LAS unsigned*)(lds + (bufoff) + ldsw + _i * 8192), 16, 0, 0); } while (0)
; #define PG8_LDA(dst, b, h) do { _Pragma("unroll") for (int m = 0; m < 4; ++m) _Pragma("unroll") for (int k = 0; k < 2; ++k) dst[m][k] = *(const PG8_LAS bf16x8*)(lds + PG8_SA(b, h) + aoff + m * 2048 + k * 1024); } while (0)
; #define PG8_MMA(ai, bj, At, Bt) do { __builtin_amdgcn_s_setprio(1); _Pragma("unroll") for (int m = 0; m < 4; ++m) _Pragma("unroll") for (int n = 0; n < 2; ++n) _Pragma("unroll") for (int k = 0; k < 2; ++k) \
;         acc[ai][bj][m][n] = __builtin_amdgcn_mfma_f32_16x16x32_bf16(Bt[n][k], At[m][k], acc[ai][bj][m][n], 0, 0, 0); __builtin_amdgcn_s_setprio(0); } while (0)
; #define PG8_WAIT_V(n) asm volatile("s_waitcnt vmcnt(" #n ")" ::: "memory")
; #define PG8_WAIT_L(n) asm volatile("s_waitcnt lgkmcnt(" #n ")" ::: "memory")
; #define PG8_BAR __builtin_amdgcn_s_barrier()
; #define PG8_SCHED __builtin_amdgcn_sched_barrier(0)
; template <class Epi, class Sched, bool ALIGN_EPI = false, bool SP2 = false>
; __device__ __forceinline__ void gemm_phase(PG8_LAS unsigned char* lds, const Gemm g, const Sched& S, const Epi& E) {
;     ...
;         for (int t = 0; t < nt; t += 2) {
;             const bool last = (t == nt - 2);
;     ...
;             PG8_LDA(At, 1, 1); PG8_STAGE(PG8_SB(1, 0), b3, voffB); PG8_STAGE(PG8_SB(1, 1), b3 + hstep, voffB); PG8_STAGE(PG8_SA(1, 0), a3, voffA);
;             PG8_WAIT_V(8); PG8_WAIT_L(0); PG8_BAR; PG8_MMA(1, 0, At, B0); PG8_MMA(1, 1, At, B1); PG8_BAR; PG8_SCHED;
	s_setprio 0
	s_add_i32 s68, s93, s0
	v_lshl_add_u64 v[150:151], v[150:151], 0, s[18:19]
	s_mov_b32 m0, s68
	ds_read_b128 v[200:203], v149 offset:49152
	ds_read_b128 v[204:207], v149 offset:50176
	ds_read_b128 v[208:211], v149 offset:51200
	ds_read_b128 v[212:215], v149 offset:52224
	ds_read_b128 v[216:219], v149 offset:53248
	ds_read_b128 v[220:223], v149 offset:54272
	ds_read_b128 v[224:227], v149 offset:55296
	ds_read_b128 v[228:231], v149 offset:56320
	global_load_lds_dwordx4 v[150:151], off
	s_add_i32 m0, s68, 0x2000
	s_add_u32 s68, s78, 0x80080
	v_lshl_add_u64 v[150:151], v[182:183], 0, s[18:19]
	s_addc_u32 s69, s79, 0
	s_add_i32 s78, s82, s0
	global_load_lds_dwordx4 v[150:151], off
	v_lshl_add_u64 v[150:151], s[68:69], 0, v[152:153]
	s_mov_b32 m0, s78
	s_nop 0
	global_load_lds_dwordx4 v[150:151], off
	v_lshl_add_u64 v[150:151], s[68:69], 0, v[128:129]
	s_add_i32 m0, s78, 0x2000
	s_nop 0
	global_load_lds_dwordx4 v[150:151], off
	v_lshl_add_u64 v[150:151], v[184:185], 0, s[18:19]
	s_mov_b32 m0, s22
	s_nop 0
	global_load_lds_dwordx4 v[150:151], off
	v_lshl_add_u64 v[150:151], v[188:189], 0, s[18:19]
	s_mov_b32 m0, s23
	s_nop 0
	global_load_lds_dwordx4 v[150:151], off
	s_waitcnt vmcnt(8)
	s_waitcnt lgkmcnt(0)
	s_setprio 1
	s_barrier
	v_mfma_f32_16x16x32_bf16 v[60:63], v[140:143], v[200:203], v[60:63]
	v_mfma_f32_16x16x32_bf16 v[56:59], v[160:163], v[200:203], v[56:59]
	v_mfma_f32_16x16x32_bf16 v[44:47], v[140:143], v[208:211], v[44:47]
	v_mfma_f32_16x16x32_bf16 v[40:43], v[160:163], v[208:211], v[40:43]
	v_mfma_f32_16x16x32_bf16 v[28:31], v[140:143], v[216:219], v[28:31]
	v_mfma_f32_16x16x32_bf16 v[24:27], v[160:163], v[216:219], v[24:27]
	v_mfma_f32_16x16x32_bf16 v[12:15], v[140:143], v[224:227], v[12:15]
	v_mfma_f32_16x16x32_bf16 v[8:11], v[160:163], v[224:227], v[8:11]
	v_mfma_f32_16x16x32_bf16 v[60:63], v[156:159], v[204:207], v[60:63]
	v_mfma_f32_16x16x32_bf16 v[56:59], v[164:167], v[204:207], v[56:59]
	v_mfma_f32_16x16x32_bf16 v[44:47], v[156:159], v[212:215], v[44:47]
	v_mfma_f32_16x16x32_bf16 v[40:43], v[164:167], v[212:215], v[40:43]
	v_mfma_f32_16x16x32_bf16 v[28:31], v[156:159], v[220:223], v[28:31]
	v_mfma_f32_16x16x32_bf16 v[24:27], v[164:167], v[220:223], v[24:27]
	v_mfma_f32_16x16x32_bf16 v[12:15], v[156:159], v[228:231], v[12:15]
	v_mfma_f32_16x16x32_bf16 v[8:11], v[164:167], v[228:231], v[8:11]
	v_mfma_f32_16x16x32_bf16 v[52:55], v[168:171], v[200:203], v[52:55]
	v_mfma_f32_16x16x32_bf16 v[48:51], v[192:195], v[200:203], v[48:51]
	v_mfma_f32_16x16x32_bf16 v[36:39], v[168:171], v[208:211], v[36:39]
	v_mfma_f32_16x16x32_bf16 v[32:35], v[192:195], v[208:211], v[32:35]
	v_mfma_f32_16x16x32_bf16 v[20:23], v[168:171], v[216:219], v[20:23]
	v_mfma_f32_16x16x32_bf16 v[16:19], v[192:195], v[216:219], v[16:19]
	v_mfma_f32_16x16x32_bf16 v[4:7], v[168:171], v[224:227], v[4:7]
	v_mfma_f32_16x16x32_bf16 v[0:3], v[192:195], v[224:227], v[0:3]
	v_mfma_f32_16x16x32_bf16 v[52:55], v[172:175], v[204:207], v[52:55]
	v_mfma_f32_16x16x32_bf16 v[48:51], v[196:199], v[204:207], v[48:51]
	v_mfma_f32_16x16x32_bf16 v[36:39], v[172:175], v[212:215], v[36:39]
	v_mfma_f32_16x16x32_bf16 v[32:35], v[196:199], v[212:215], v[32:35]
	v_mfma_f32_16x16x32_bf16 v[20:23], v[172:175], v[220:223], v[20:23]
	v_mfma_f32_16x16x32_bf16 v[16:19], v[196:199], v[220:223], v[16:19]
	v_mfma_f32_16x16x32_bf16 v[4:7], v[172:175], v[228:231], v[4:7]
	v_mfma_f32_16x16x32_bf16 v[0:3], v[196:199], v[228:231], v[0:3]
	s_add_i32 s71, s71, 2
	s_add_u32 s42, s42, 0x100
	s_addc_u32 s43, s43, 0
	s_add_u32 s59, s59, 0x100
	s_addc_u32 s63, s63, 0
	s_cmp_gt_u32 s71, 29
	s_cbranch_scc1 .Llastbar_165
	s_barrier
	s_setprio 0
	s_branch .LBB0_165
.Llastbar_165:
	s_setprio 0

; #define PG8_STAGE(bufoff, gbase, voff) do { _Pragma("unroll") for (int _i = 0; _i < 2; ++_i) \
;         __builtin_amdgcn_global_load_lds((const unsigned*)((const char*)(gbase) + (voff)[_i]), (PG8_LAS unsigned*)(lds + (bufoff) + ldsw + _i * 8192), 16, 0, 0); } while (0)
; #define PG8_LDA(dst, b, h) do { _Pragma("unroll") for (int m = 0; m < 4; ++m) _Pragma("unroll") for (int k = 0; k < 2; ++k) dst[m][k] = *(const PG8_LAS bf16x8*)(lds + PG8_SA(b, h) + aoff + m * 2048 + k * 1024); } while (0)
; #define PG8_LDB(dst, b, h) do { _Pragma("unroll") for (int n = 0; n < 2; ++n) _Pragma("unroll") for (int k = 0; k < 2; ++k) dst[n][k] = *(const PG8_LAS bf16x8*)(lds + PG8_SB(b, h) + boff + n * 2048 + k * 1024); } while (0)
; #define PG8_MMA(ai, bj, At, Bt) do { __builtin_amdgcn_s_setprio(1); _Pragma("unroll") for (int m = 0; m < 4; ++m) _Pragma("unroll") for (int n = 0; n < 2; ++n) _Pragma("unroll") for (int k = 0; k < 2; ++k) \
;         acc[ai][bj][m][n] = __builtin_amdgcn_mfma_f32_16x16x32_bf16(Bt[n][k], At[m][k], acc[ai][bj][m][n], 0, 0, 0); __builtin_amdgcn_s_setprio(0); } while (0)
; #define PG8_WAIT_V(n) asm volatile("s_waitcnt vmcnt(" #n ")" ::: "memory")
; #define PG8_WAIT_L(n) asm volatile("s_waitcnt lgkmcnt(" #n ")" ::: "memory")
; #define PG8_BAR __builtin_amdgcn_s_barrier()
; #define PG8_SCHED __builtin_amdgcn_sched_barrier(0)
; template <class Epi, class Sched, bool ALIGN_EPI = false, bool SP2 = false>
; __device__ __forceinline__ void gemm_phase(PG8_LAS unsigned char* lds, const Gemm g, const Sched& S, const Epi& E) {
;     ...
;             PG8_LDB(B0, 0, 0); PG8_LDB(B1, 0, 1); PG8_SCHED; PG8_LDA(At, 0, 0); PG8_STAGE(PG8_SA(1, 1), a1 + hstep, voffA);
;             PG8_WAIT_V(8); PG8_WAIT_L(0); PG8_BAR; PG8_MMA(0, 0, At, B0); PG8_MMA(0, 1, At, B1); PG8_BAR; PG8_SCHED;
;             PG8_LDA(At, 0, 1); PG8_STAGE(PG8_SB(0, 0), b2, voffB); PG8_STAGE(PG8_SB(0, 1), b2 + hstep, voffB); PG8_STAGE(PG8_SA(0, 0), a2, voffA);
;             PG8_WAIT_V(8); PG8_WAIT_L(0); PG8_BAR; PG8_MMA(1, 0, At, B0); PG8_MMA(1, 1, At, B1); PG8_BAR; PG8_SCHED;
.LBB0_218:
	s_add_i32 vcc_lo, s46, 2
	s_add_u32 s68, s44, 0x80
	s_addc_u32 s47, s45, 0
	s_add_i32 vcc_hi, 0, 0x10000
	s_cmp_eq_u32 s15, s46
	s_cselect_b32 s47, s83, s47
	s_cselect_b32 s46, s82, s68
	v_add_u32_e32 v146, vcc_hi, v149
	s_cselect_b32 s69, s85, s87
	s_cselect_b32 s68, s84, s86
	s_add_i32 s96, 0, 0x14000
	ds_read_b128 v[138:141], v146
	ds_read_b128 v[142:145], v146 offset:1024
	ds_read_b128 v[156:159], v146 offset:2048
	ds_read_b128 v[160:163], v146 offset:3072
	v_add_u32_e32 v146, s96, v149
	ds_read_b128 v[164:167], v146
	ds_read_b128 v[168:171], v146 offset:1024
	ds_read_b128 v[172:175], v146 offset:2048
	ds_read_b128 v[192:195], v146 offset:3072
	v_lshl_add_u64 v[146:147], s[44:45], 0, v[134:135]
	s_add_i32 m0, s54, 0xc000
	ds_read_b128 v[196:199], v151
	ds_read_b128 v[200:203], v151 offset:1024
	ds_read_b128 v[204:207], v151 offset:2048
	ds_read_b128 v[208:211], v151 offset:3072
	ds_read_b128 v[212:215], v151 offset:4096
	ds_read_b128 v[216:219], v151 offset:5120
	ds_read_b128 v[220:223], v151 offset:6144
	ds_read_b128 v[224:227], v151 offset:7168
	global_load_lds_dwordx4 v[146:147], off
	v_lshl_add_u64 v[146:147], s[44:45], 0, v[136:137]
	s_add_i32 m0, s54, 0xe000
	s_nop 0
	global_load_lds_dwordx4 v[146:147], off
	s_waitcnt vmcnt(8)
	s_waitcnt lgkmcnt(0)
	s_setprio 1
	s_barrier
	v_mfma_f32_16x16x32_bf16 v[124:127], v[138:141], v[196:199], v[124:127]
	v_mfma_f32_16x16x32_bf16 v[120:123], v[156:159], v[196:199], v[120:123]
	v_mfma_f32_16x16x32_bf16 v[108:111], v[138:141], v[204:207], v[108:111]
	v_mfma_f32_16x16x32_bf16 v[104:107], v[156:159], v[204:207], v[104:107]
	v_mfma_f32_16x16x32_bf16 v[92:95], v[138:141], v[212:215], v[92:95]
	v_mfma_f32_16x16x32_bf16 v[88:91], v[156:159], v[212:215], v[88:91]
	v_mfma_f32_16x16x32_bf16 v[76:79], v[138:141], v[220:223], v[76:79]
	v_mfma_f32_16x16x32_bf16 v[72:75], v[156:159], v[220:223], v[72:75]
	v_mfma_f32_16x16x32_bf16 v[124:127], v[142:145], v[200:203], v[124:127]
	v_mfma_f32_16x16x32_bf16 v[120:123], v[160:163], v[200:203], v[120:123]
	v_mfma_f32_16x16x32_bf16 v[108:111], v[142:145], v[208:211], v[108:111]
	v_mfma_f32_16x16x32_bf16 v[104:107], v[160:163], v[208:211], v[104:107]
	v_mfma_f32_16x16x32_bf16 v[92:95], v[142:145], v[216:219], v[92:95]
	v_mfma_f32_16x16x32_bf16 v[88:91], v[160:163], v[216:219], v[88:91]
	v_mfma_f32_16x16x32_bf16 v[76:79], v[142:145], v[224:227], v[76:79]
	v_mfma_f32_16x16x32_bf16 v[72:75], v[160:163], v[224:227], v[72:75]
	v_mfma_f32_16x16x32_bf16 v[116:119], v[164:167], v[196:199], v[116:119]
	v_mfma_f32_16x16x32_bf16 v[112:115], v[172:175], v[196:199], v[112:115]
	v_mfma_f32_16x16x32_bf16 v[100:103], v[164:167], v[204:207], v[100:103]
	v_mfma_f32_16x16x32_bf16 v[96:99], v[172:175], v[204:207], v[96:99]
	v_mfma_f32_16x16x32_bf16 v[84:87], v[164:167], v[212:215], v[84:87]
	v_mfma_f32_16x16x32_bf16 v[80:83], v[172:175], v[212:215], v[80:83]
	v_mfma_f32_16x16x32_bf16 v[68:71], v[164:167], v[220:223], v[68:71]
	v_mfma_f32_16x16x32_bf16 v[64:67], v[172:175], v[220:223], v[64:67]
	v_mfma_f32_16x16x32_bf16 v[116:119], v[168:171], v[200:203], v[116:119]
	v_mfma_f32_16x16x32_bf16 v[112:115], v[192:195], v[200:203], v[112:115]
	v_mfma_f32_16x16x32_bf16 v[100:103], v[168:171], v[208:211], v[100:103]
	v_mfma_f32_16x16x32_bf16 v[96:99], v[192:195], v[208:211], v[96:99]
	v_mfma_f32_16x16x32_bf16 v[84:87], v[168:171], v[216:219], v[84:87]
	v_mfma_f32_16x16x32_bf16 v[80:83], v[192:195], v[216:219], v[80:83]
	v_mfma_f32_16x16x32_bf16 v[68:71], v[168:171], v[224:227], v[68:71]
	v_mfma_f32_16x16x32_bf16 v[64:67], v[192:195], v[224:227], v[64:67]
	s_barrier
	s_setprio 0
	s_add_i32 vcc_hi, vcc_hi, s63
	v_lshl_add_u64 v[146:147], s[68:69], 0, v[152:153]
	s_mov_b32 m0, vcc_hi
	ds_read_b128 v[196:199], v151 offset:16384
	ds_read_b128 v[200:203], v151 offset:17408
	ds_read_b128 v[204:207], v151 offset:18432
	ds_read_b128 v[208:211], v151 offset:19456
	ds_read_b128 v[212:215], v151 offset:20480
	ds_read_b128 v[216:219], v151 offset:21504
	ds_read_b128 v[220:223], v151 offset:22528
	ds_read_b128 v[224:227], v151 offset:23552
	global_load_lds_dwordx4 v[146:147], off
	s_add_i32 m0, vcc_hi, 0x2000
	v_lshl_add_u64 v[182:183], s[68:69], 0, v[128:129]
	s_add_u32 s68, s68, s48
	s_addc_u32 s69, s69, 0
	s_add_i32 s96, s96, s63
	global_load_lds_dwordx4 v[182:183], off
	v_lshl_add_u64 v[184:185], s[68:69], 0, v[152:153]
	s_mov_b32 m0, s96
	v_lshl_add_u64 v[188:189], s[68:69], 0, v[128:129]
	global_load_lds_dwordx4 v[184:185], off
	s_add_i32 m0, s96, 0x2000
	v_lshl_add_u64 v[190:191], s[46:47], 0, v[132:133]
	global_load_lds_dwordx4 v[188:189], off
	s_mov_b32 m0, s54
	v_lshl_add_u64 v[228:229], s[46:47], 0, v[130:131]
	global_load_lds_dwordx4 v[190:191], off
	s_mov_b32 m0, s55
	s_nop 0
	global_load_lds_dwordx4 v[228:229], off
	s_waitcnt vmcnt(8)
	s_waitcnt lgkmcnt(0)
	s_setprio 1
	s_barrier
; #define PG8_STAGE(bufoff, gbase, voff) do { _Pragma("unroll") for (int _i = 0; _i < 2; ++_i) \
;         __builtin_amdgcn_global_load_lds((const unsigned*)((const char*)(gbase) + (voff)[_i]), (PG8_LAS unsigned*)(lds + (bufoff) + ldsw + _i * 8192), 16, 0, 0); } while (0)
; #define PG8_LDA(dst, b, h) do { _Pragma("unroll") for (int m = 0; m < 4; ++m) _Pragma("unroll") for (int k = 0; k < 2; ++k) dst[m][k] = *(const PG8_LAS bf16x8*)(lds + PG8_SA(b, h) + aoff + m * 2048 + k * 1024); } while (0)
; #define PG8_LDB(dst, b, h) do { _Pragma("unroll") for (int n = 0; n < 2; ++n) _Pragma("unroll") for (int k = 0; k < 2; ++k) dst[n][k] = *(const PG8_LAS bf16x8*)(lds + PG8_SB(b, h) + boff + n * 2048 + k * 1024); } while (0)
; #define PG8_MMA(ai, bj, At, Bt) do { __builtin_amdgcn_s_setprio(1); _Pragma("unroll") for (int m = 0; m < 4; ++m) _Pragma("unroll") for (int n = 0; n < 2; ++n) _Pragma("unroll") for (int k = 0; k < 2; ++k) \
;         acc[ai][bj][m][n] = __builtin_amdgcn_mfma_f32_16x16x32_bf16(Bt[n][k], At[m][k], acc[ai][bj][m][n], 0, 0, 0); __builtin_amdgcn_s_setprio(0); } while (0)
; #define PG8_WAIT_V(n) asm volatile("s_waitcnt vmcnt(" #n ")" ::: "memory")
; #define PG8_WAIT_L(n) asm volatile("s_waitcnt lgkmcnt(" #n ")" ::: "memory")
; #define PG8_BAR __builtin_amdgcn_s_barrier()
; #define PG8_SCHED __builtin_amdgcn_sched_barrier(0)
; template <class Epi, class Sched, bool ALIGN_EPI = false, bool SP2 = false>
; __device__ __forceinline__ void gemm_phase(PG8_LAS unsigned char* lds, const Gemm g, const Sched& S, const Epi& E) {
;     ...
;             PG8_WAIT_V(8); PG8_WAIT_L(0); PG8_BAR; PG8_MMA(1, 0, At, B0); PG8_MMA(1, 1, At, B1); PG8_BAR; PG8_SCHED;
;             PG8_LDB(B0, 1, 0); PG8_LDB(B1, 1, 1); PG8_SCHED; PG8_LDA(At, 1, 0); PG8_STAGE(PG8_SA(0, 1), a2 + hstep, voffA);
;             PG8_WAIT_V(8); PG8_WAIT_L(0); PG8_BAR; PG8_MMA(0, 0, At, B0); PG8_MMA(0, 1, At, B1); PG8_BAR; PG8_SCHED;
;             PG8_LDA(At, 1, 1); PG8_STAGE(PG8_SB(1, 0), b3, voffB); PG8_STAGE(PG8_SB(1, 1), b3 + hstep, voffB); PG8_STAGE(PG8_SA(1, 0), a3, voffA);
	v_mfma_f32_16x16x32_bf16 v[60:63], v[138:141], v[196:199], v[60:63]
	v_mfma_f32_16x16x32_bf16 v[56:59], v[156:159], v[196:199], v[56:59]
	v_mfma_f32_16x16x32_bf16 v[44:47], v[138:141], v[204:207], v[44:47]
	v_mfma_f32_16x16x32_bf16 v[40:43], v[156:159], v[204:207], v[40:43]
	v_mfma_f32_16x16x32_bf16 v[28:31], v[138:141], v[212:215], v[28:31]
	v_mfma_f32_16x16x32_bf16 v[24:27], v[156:159], v[212:215], v[24:27]
	v_mfma_f32_16x16x32_bf16 v[12:15], v[138:141], v[220:223], v[12:15]
	v_mfma_f32_16x16x32_bf16 v[8:11], v[156:159], v[220:223], v[8:11]
	v_mfma_f32_16x16x32_bf16 v[60:63], v[142:145], v[200:203], v[60:63]
	v_mfma_f32_16x16x32_bf16 v[56:59], v[160:163], v[200:203], v[56:59]
	v_mfma_f32_16x16x32_bf16 v[44:47], v[142:145], v[208:211], v[44:47]
	v_mfma_f32_16x16x32_bf16 v[40:43], v[160:163], v[208:211], v[40:43]
	v_mfma_f32_16x16x32_bf16 v[28:31], v[142:145], v[216:219], v[28:31]
	v_mfma_f32_16x16x32_bf16 v[24:27], v[160:163], v[216:219], v[24:27]
	v_mfma_f32_16x16x32_bf16 v[12:15], v[142:145], v[224:227], v[12:15]
	v_mfma_f32_16x16x32_bf16 v[8:11], v[160:163], v[224:227], v[8:11]
	v_mfma_f32_16x16x32_bf16 v[52:55], v[164:167], v[196:199], v[52:55]
	v_mfma_f32_16x16x32_bf16 v[48:51], v[172:175], v[196:199], v[48:51]
	v_mfma_f32_16x16x32_bf16 v[36:39], v[164:167], v[204:207], v[36:39]
	v_mfma_f32_16x16x32_bf16 v[32:35], v[172:175], v[204:207], v[32:35]
	v_mfma_f32_16x16x32_bf16 v[20:23], v[164:167], v[212:215], v[20:23]
	v_mfma_f32_16x16x32_bf16 v[16:19], v[172:175], v[212:215], v[16:19]
	v_mfma_f32_16x16x32_bf16 v[4:7], v[164:167], v[220:223], v[4:7]
	v_mfma_f32_16x16x32_bf16 v[0:3], v[172:175], v[220:223], v[0:3]
	v_mfma_f32_16x16x32_bf16 v[52:55], v[168:171], v[200:203], v[52:55]
	v_mfma_f32_16x16x32_bf16 v[48:51], v[192:195], v[200:203], v[48:51]
	v_mfma_f32_16x16x32_bf16 v[36:39], v[168:171], v[208:211], v[36:39]
	v_mfma_f32_16x16x32_bf16 v[32:35], v[192:195], v[208:211], v[32:35]
	v_mfma_f32_16x16x32_bf16 v[20:23], v[168:171], v[216:219], v[20:23]
	v_mfma_f32_16x16x32_bf16 v[16:19], v[192:195], v[216:219], v[16:19]
	v_mfma_f32_16x16x32_bf16 v[4:7], v[168:171], v[224:227], v[4:7]
	v_mfma_f32_16x16x32_bf16 v[0:3], v[192:195], v[224:227], v[0:3]
	s_barrier
	s_setprio 0
	v_add_u32_e32 v155, s93, v149
	s_add_i32 s68, 0, 0x1c000
	ds_read_b128 v[138:141], v155
	ds_read_b128 v[142:145], v155 offset:1024
	ds_read_b128 v[156:159], v155 offset:2048
	ds_read_b128 v[160:163], v155 offset:3072
	v_add_u32_e32 v155, s68, v149
	ds_read_b128 v[164:167], v155
	ds_read_b128 v[168:171], v155 offset:1024
	ds_read_b128 v[172:175], v155 offset:2048
	ds_read_b128 v[192:195], v155 offset:3072
	s_add_u32 s46, s46, s48
	s_addc_u32 s47, s47, 0
	s_mov_b32 m0, s34
	v_lshl_add_u64 v[230:231], s[46:47], 0, v[132:133]
	ds_read_b128 v[196:199], v151 offset:32768
	ds_read_b128 v[200:203], v151 offset:33792
	ds_read_b128 v[204:207], v151 offset:34816
	ds_read_b128 v[208:211], v151 offset:35840
	ds_read_b128 v[212:215], v151 offset:36864
	ds_read_b128 v[216:219], v151 offset:37888
	ds_read_b128 v[220:223], v151 offset:38912
	ds_read_b128 v[224:227], v151 offset:39936
	global_load_lds_dwordx4 v[230:231], off
	v_lshl_add_u64 v[230:231], s[46:47], 0, v[130:131]
	s_mov_b32 m0, s95
	s_nop 0
	global_load_lds_dwordx4 v[230:231], off
	s_waitcnt vmcnt(8)
	s_waitcnt lgkmcnt(0)
	s_setprio 1
	s_barrier
	v_mfma_f32_16x16x32_bf16 v[124:127], v[138:141], v[196:199], v[124:127]
	v_mfma_f32_16x16x32_bf16 v[120:123], v[156:159], v[196:199], v[120:123]
	v_mfma_f32_16x16x32_bf16 v[108:111], v[138:141], v[204:207], v[108:111]
	v_mfma_f32_16x16x32_bf16 v[104:107], v[156:159], v[204:207], v[104:107]
	v_mfma_f32_16x16x32_bf16 v[92:95], v[138:141], v[212:215], v[92:95]
	v_mfma_f32_16x16x32_bf16 v[88:91], v[156:159], v[212:215], v[88:91]
	v_mfma_f32_16x16x32_bf16 v[76:79], v[138:141], v[220:223], v[76:79]
	v_mfma_f32_16x16x32_bf16 v[72:75], v[156:159], v[220:223], v[72:75]
	v_mfma_f32_16x16x32_bf16 v[124:127], v[142:145], v[200:203], v[124:127]
	v_mfma_f32_16x16x32_bf16 v[120:123], v[160:163], v[200:203], v[120:123]
	v_mfma_f32_16x16x32_bf16 v[108:111], v[142:145], v[208:211], v[108:111]
	v_mfma_f32_16x16x32_bf16 v[104:107], v[160:163], v[208:211], v[104:107]
	v_mfma_f32_16x16x32_bf16 v[92:95], v[142:145], v[216:219], v[92:95]
	v_mfma_f32_16x16x32_bf16 v[88:91], v[160:163], v[216:219], v[88:91]
	v_mfma_f32_16x16x32_bf16 v[76:79], v[142:145], v[224:227], v[76:79]
	v_mfma_f32_16x16x32_bf16 v[72:75], v[160:163], v[224:227], v[72:75]
	v_mfma_f32_16x16x32_bf16 v[116:119], v[164:167], v[196:199], v[116:119]
	v_mfma_f32_16x16x32_bf16 v[112:115], v[172:175], v[196:199], v[112:115]
	v_mfma_f32_16x16x32_bf16 v[100:103], v[164:167], v[204:207], v[100:103]
	v_mfma_f32_16x16x32_bf16 v[96:99], v[172:175], v[204:207], v[96:99]
	v_mfma_f32_16x16x32_bf16 v[84:87], v[164:167], v[212:215], v[84:87]
	v_mfma_f32_16x16x32_bf16 v[80:83], v[172:175], v[212:215], v[80:83]
	v_mfma_f32_16x16x32_bf16 v[68:71], v[164:167], v[220:223], v[68:71]
	v_mfma_f32_16x16x32_bf16 v[64:67], v[172:175], v[220:223], v[64:67]
	v_mfma_f32_16x16x32_bf16 v[116:119], v[168:171], v[200:203], v[116:119]
	v_mfma_f32_16x16x32_bf16 v[112:115], v[192:195], v[200:203], v[112:115]
	v_mfma_f32_16x16x32_bf16 v[100:103], v[168:171], v[208:211], v[100:103]
	v_mfma_f32_16x16x32_bf16 v[96:99], v[192:195], v[208:211], v[96:99]
	v_mfma_f32_16x16x32_bf16 v[84:87], v[168:171], v[216:219], v[84:87]
	v_mfma_f32_16x16x32_bf16 v[80:83], v[192:195], v[216:219], v[80:83]
	v_mfma_f32_16x16x32_bf16 v[68:71], v[168:171], v[224:227], v[68:71]
	v_mfma_f32_16x16x32_bf16 v[64:67], v[192:195], v[224:227], v[64:67]
	s_barrier
; #define PG8_STAGE(bufoff, gbase, voff) do { _Pragma("unroll") for (int _i = 0; _i < 2; ++_i) \
;         __builtin_amdgcn_global_load_lds((const unsigned*)((const char*)(gbase) + (voff)[_i]), (PG8_LAS unsigned*)(lds + (bufoff) + ldsw + _i * 8192), 16, 0, 0); } while (0)
; #define PG8_LDA(dst, b, h) do { _Pragma("unroll") for (int m = 0; m < 4; ++m) _Pragma("unroll") for (int k = 0; k < 2; ++k) dst[m][k] = *(const PG8_LAS bf16x8*)(lds + PG8_SA(b, h) + aoff + m * 2048 + k * 1024); } while (0)
; #define PG8_MMA(ai, bj, At, Bt) do { __builtin_amdgcn_s_setprio(1); _Pragma("unroll") for (int m = 0; m < 4; ++m) _Pragma("unroll") for (int n = 0; n < 2; ++n) _Pragma("unroll") for (int k = 0; k < 2; ++k) \
;         acc[ai][bj][m][n] = __builtin_amdgcn_mfma_f32_16x16x32_bf16(Bt[n][k], At[m][k], acc[ai][bj][m][n], 0, 0, 0); __builtin_amdgcn_s_setprio(0); } while (0)
; #define PG8_WAIT_V(n) asm volatile("s_waitcnt vmcnt(" #n ")" ::: "memory")
; #define PG8_WAIT_L(n) asm volatile("s_waitcnt lgkmcnt(" #n ")" ::: "memory")
; #define PG8_BAR __builtin_amdgcn_s_barrier()
; #define PG8_SCHED __builtin_amdgcn_sched_barrier(0)
; template <class Epi, class Sched, bool ALIGN_EPI = false, bool SP2 = false>
; __device__ __forceinline__ void gemm_phase(PG8_LAS unsigned char* lds, const Gemm g, const Sched& S, const Epi& E) {
;     ...
;         for (int t = 0; t < nt; t += 2) {
;             const bool last = (t == nt - 2);
;     ...
;             PG8_LDA(At, 1, 1); PG8_STAGE(PG8_SB(1, 0), b3, voffB); PG8_STAGE(PG8_SB(1, 1), b3 + hstep, voffB); PG8_STAGE(PG8_SA(1, 0), a3, voffA);
;             PG8_WAIT_V(8); PG8_WAIT_L(0); PG8_BAR; PG8_MMA(1, 0, At, B0); PG8_MMA(1, 1, At, B1); PG8_BAR; PG8_SCHED;
	s_setprio 0
	s_add_i32 s46, s93, s63
	v_lshl_add_u64 v[146:147], v[146:147], 0, s[18:19]
	s_mov_b32 m0, s46
	ds_read_b128 v[196:199], v151 offset:49152
	ds_read_b128 v[200:203], v151 offset:50176
	ds_read_b128 v[204:207], v151 offset:51200
	ds_read_b128 v[208:211], v151 offset:52224
	ds_read_b128 v[212:215], v151 offset:53248
	ds_read_b128 v[216:219], v151 offset:54272
	ds_read_b128 v[220:223], v151 offset:55296
	ds_read_b128 v[224:227], v151 offset:56320
	global_load_lds_dwordx4 v[146:147], off
	v_lshl_add_u64 v[146:147], v[182:183], 0, s[18:19]
	s_add_i32 m0, s46, 0x2000
	s_add_i32 s46, s68, s63
	global_load_lds_dwordx4 v[146:147], off
	v_lshl_add_u64 v[146:147], v[184:185], 0, s[18:19]
	s_mov_b32 m0, s46
	s_nop 0
	global_load_lds_dwordx4 v[146:147], off
	v_lshl_add_u64 v[146:147], v[188:189], 0, s[18:19]
	s_add_i32 m0, s46, 0x2000
	s_nop 0
	global_load_lds_dwordx4 v[146:147], off
	v_lshl_add_u64 v[146:147], v[190:191], 0, s[18:19]
	s_mov_b32 m0, s0
	s_nop 0
	global_load_lds_dwordx4 v[146:147], off
	v_lshl_add_u64 v[146:147], v[228:229], 0, s[18:19]
	s_mov_b32 m0, s58
	s_nop 0
	global_load_lds_dwordx4 v[146:147], off
	s_waitcnt vmcnt(8)
	s_waitcnt lgkmcnt(0)
	s_setprio 1
	s_barrier
	v_mfma_f32_16x16x32_bf16 v[60:63], v[138:141], v[196:199], v[60:63]
	v_mfma_f32_16x16x32_bf16 v[56:59], v[156:159], v[196:199], v[56:59]
	v_mfma_f32_16x16x32_bf16 v[44:47], v[138:141], v[204:207], v[44:47]
	v_mfma_f32_16x16x32_bf16 v[40:43], v[156:159], v[204:207], v[40:43]
	v_mfma_f32_16x16x32_bf16 v[28:31], v[138:141], v[212:215], v[28:31]
	v_mfma_f32_16x16x32_bf16 v[24:27], v[156:159], v[212:215], v[24:27]
	v_mfma_f32_16x16x32_bf16 v[12:15], v[138:141], v[220:223], v[12:15]
	v_mfma_f32_16x16x32_bf16 v[8:11], v[156:159], v[220:223], v[8:11]
	v_mfma_f32_16x16x32_bf16 v[60:63], v[142:145], v[200:203], v[60:63]
	v_mfma_f32_16x16x32_bf16 v[56:59], v[160:163], v[200:203], v[56:59]
	v_mfma_f32_16x16x32_bf16 v[44:47], v[142:145], v[208:211], v[44:47]
	v_mfma_f32_16x16x32_bf16 v[40:43], v[160:163], v[208:211], v[40:43]
	v_mfma_f32_16x16x32_bf16 v[28:31], v[142:145], v[216:219], v[28:31]
	v_mfma_f32_16x16x32_bf16 v[24:27], v[160:163], v[216:219], v[24:27]
	v_mfma_f32_16x16x32_bf16 v[12:15], v[142:145], v[224:227], v[12:15]
	v_mfma_f32_16x16x32_bf16 v[8:11], v[160:163], v[224:227], v[8:11]
	v_mfma_f32_16x16x32_bf16 v[52:55], v[164:167], v[196:199], v[52:55]
	v_mfma_f32_16x16x32_bf16 v[48:51], v[172:175], v[196:199], v[48:51]
	v_mfma_f32_16x16x32_bf16 v[36:39], v[164:167], v[204:207], v[36:39]
	v_mfma_f32_16x16x32_bf16 v[32:35], v[172:175], v[204:207], v[32:35]
	v_mfma_f32_16x16x32_bf16 v[20:23], v[164:167], v[212:215], v[20:23]
	v_mfma_f32_16x16x32_bf16 v[16:19], v[172:175], v[212:215], v[16:19]
	v_mfma_f32_16x16x32_bf16 v[4:7], v[164:167], v[220:223], v[4:7]
	v_mfma_f32_16x16x32_bf16 v[0:3], v[172:175], v[220:223], v[0:3]
	v_mfma_f32_16x16x32_bf16 v[52:55], v[168:171], v[200:203], v[52:55]
	v_mfma_f32_16x16x32_bf16 v[48:51], v[192:195], v[200:203], v[48:51]
	v_mfma_f32_16x16x32_bf16 v[36:39], v[168:171], v[208:211], v[36:39]
	v_mfma_f32_16x16x32_bf16 v[32:35], v[192:195], v[208:211], v[32:35]
	v_mfma_f32_16x16x32_bf16 v[20:23], v[168:171], v[216:219], v[20:23]
	v_mfma_f32_16x16x32_bf16 v[16:19], v[192:195], v[216:219], v[16:19]
	v_mfma_f32_16x16x32_bf16 v[4:7], v[168:171], v[224:227], v[4:7]
	v_mfma_f32_16x16x32_bf16 v[0:3], v[192:195], v[224:227], v[0:3]
	s_add_u32 s44, s44, 0x100
	s_addc_u32 s45, s45, 0
	s_add_u32 s86, s86, 0x100
	s_addc_u32 s87, s87, 0
	s_cmp_ge_u32 vcc_lo, s14
	s_mov_b32 s46, vcc_lo
	s_cbranch_scc1 .Llastbar_218
	s_barrier
	s_setprio 0
	s_branch .LBB0_218

; #define PG8_STAGE(bufoff, gbase, voff) do { _Pragma("unroll") for (int _i = 0; _i < 2; ++_i) \
;         __builtin_amdgcn_global_load_lds((const unsigned*)((const char*)(gbase) + (voff)[_i]), (PG8_LAS unsigned*)(lds + (bufoff) + ldsw + _i * 8192), 16, 0, 0); } while (0)
; #define PG8_LDA(dst, b, h) do { _Pragma("unroll") for (int m = 0; m < 4; ++m) _Pragma("unroll") for (int k = 0; k < 2; ++k) dst[m][k] = *(const PG8_LAS bf16x8*)(lds + PG8_SA(b, h) + aoff + m * 2048 + k * 1024); } while (0)
; #define PG8_LDB(dst, b, h) do { _Pragma("unroll") for (int n = 0; n < 2; ++n) _Pragma("unroll") for (int k = 0; k < 2; ++k) dst[n][k] = *(const PG8_LAS bf16x8*)(lds + PG8_SB(b, h) + boff + n * 2048 + k * 1024); } while (0)
; #define PG8_MMA(ai, bj, At, Bt) do { __builtin_amdgcn_s_setprio(1); _Pragma("unroll") for (int m = 0; m < 4; ++m) _Pragma("unroll") for (int n = 0; n < 2; ++n) _Pragma("unroll") for (int k = 0; k < 2; ++k) \
;         acc[ai][bj][m][n] = __builtin_amdgcn_mfma_f32_16x16x32_bf16(Bt[n][k], At[m][k], acc[ai][bj][m][n], 0, 0, 0); __builtin_amdgcn_s_setprio(0); } while (0)
; #define PG8_WAIT_V(n) asm volatile("s_waitcnt vmcnt(" #n ")" ::: "memory")
; #define PG8_WAIT_L(n) asm volatile("s_waitcnt lgkmcnt(" #n ")" ::: "memory")
; #define PG8_BAR __builtin_amdgcn_s_barrier()
; #define PG8_SCHED __builtin_amdgcn_sched_barrier(0)
; template <class Epi, class Sched, bool ALIGN_EPI = false, bool SP2 = false>
; __device__ __forceinline__ void gemm_phase(PG8_LAS unsigned char* lds, const Gemm g, const Sched& S, const Epi& E) {
;     ...
;             PG8_LDB(B0, 0, 0); PG8_LDB(B1, 0, 1); PG8_SCHED; PG8_LDA(At, 0, 0); PG8_STAGE(PG8_SA(1, 1), a1 + hstep, voffA);
;             PG8_WAIT_V(8); PG8_WAIT_L(0); PG8_BAR; PG8_MMA(0, 0, At, B0); PG8_MMA(0, 1, At, B1); PG8_BAR; PG8_SCHED;
;             PG8_LDA(At, 0, 1); PG8_STAGE(PG8_SB(0, 0), b2, voffB); PG8_STAGE(PG8_SB(0, 1), b2 + hstep, voffB); PG8_STAGE(PG8_SA(0, 0), a2, voffA);
;             PG8_WAIT_V(8); PG8_WAIT_L(0); PG8_BAR; PG8_MMA(1, 0, At, B0); PG8_MMA(1, 1, At, B1); PG8_BAR; PG8_SCHED;
.LBB0_331:
	s_add_u32 s68, s74, 0xfff80080
	s_addc_u32 s69, s75, -1
	s_add_i32 s82, 0, 0x10000
	s_cmp_eq_u32 s81, 28
	s_cselect_b32 s79, s45, s69
	s_cselect_b32 s78, s59, s68
	v_add_u32_e32 v140, s82, v143
	s_cselect_b32 s77, s43, s80
	s_cselect_b32 s76, s63, s71
	s_add_i32 s68, 0, 0x14000
	ds_read_b128 v[146:149], v140
	ds_read_b128 v[156:159], v140 offset:1024
	ds_read_b128 v[160:163], v140 offset:2048
	ds_read_b128 v[164:167], v140 offset:3072
	v_add_u32_e32 v140, s68, v143
	ds_read_b128 v[168:171], v140
	ds_read_b128 v[172:175], v140 offset:1024
	ds_read_b128 v[192:195], v140 offset:2048
	ds_read_b128 v[196:199], v140 offset:3072
	v_lshl_add_u64 v[140:141], s[74:75], 0, v[136:137]
	s_add_i32 m0, s16, 0xc000
	ds_read_b128 v[200:203], v145
	ds_read_b128 v[204:207], v145 offset:1024
	ds_read_b128 v[208:211], v145 offset:2048
	ds_read_b128 v[212:215], v145 offset:3072
	ds_read_b128 v[216:219], v145 offset:4096
	ds_read_b128 v[220:223], v145 offset:5120
	ds_read_b128 v[224:227], v145 offset:6144
	ds_read_b128 v[228:231], v145 offset:7168
	global_load_lds_dwordx4 v[140:141], off
	v_lshl_add_u64 v[140:141], s[74:75], 0, v[138:139]
	s_add_i32 m0, s16, 0xe000
	s_nop 0
	global_load_lds_dwordx4 v[140:141], off
	s_waitcnt vmcnt(8)
	s_waitcnt lgkmcnt(0)
	s_setprio 1
	s_barrier
	v_mfma_f32_16x16x32_bf16 v[116:119], v[146:149], v[200:203], v[116:119]
	v_mfma_f32_16x16x32_bf16 v[112:115], v[160:163], v[200:203], v[112:115]
	v_mfma_f32_16x16x32_bf16 v[104:107], v[146:149], v[208:211], v[104:107]
	v_mfma_f32_16x16x32_bf16 v[96:99], v[160:163], v[208:211], v[96:99]
	v_mfma_f32_16x16x32_bf16 v[88:91], v[146:149], v[216:219], v[88:91]
	v_mfma_f32_16x16x32_bf16 v[80:83], v[160:163], v[216:219], v[80:83]
	v_mfma_f32_16x16x32_bf16 v[72:75], v[146:149], v[224:227], v[72:75]
	v_mfma_f32_16x16x32_bf16 v[64:67], v[160:163], v[224:227], v[64:67]
	v_mfma_f32_16x16x32_bf16 v[116:119], v[156:159], v[204:207], v[116:119]
	v_mfma_f32_16x16x32_bf16 v[112:115], v[164:167], v[204:207], v[112:115]
	v_mfma_f32_16x16x32_bf16 v[104:107], v[156:159], v[212:215], v[104:107]
	v_mfma_f32_16x16x32_bf16 v[96:99], v[164:167], v[212:215], v[96:99]
	v_mfma_f32_16x16x32_bf16 v[88:91], v[156:159], v[220:223], v[88:91]
	v_mfma_f32_16x16x32_bf16 v[80:83], v[164:167], v[220:223], v[80:83]
	v_mfma_f32_16x16x32_bf16 v[72:75], v[156:159], v[228:231], v[72:75]
	v_mfma_f32_16x16x32_bf16 v[64:67], v[164:167], v[228:231], v[64:67]
	v_mfma_f32_16x16x32_bf16 v[124:127], v[168:171], v[200:203], v[124:127]
	v_mfma_f32_16x16x32_bf16 v[120:123], v[192:195], v[200:203], v[120:123]
	v_mfma_f32_16x16x32_bf16 v[108:111], v[168:171], v[208:211], v[108:111]
	v_mfma_f32_16x16x32_bf16 v[100:103], v[192:195], v[208:211], v[100:103]
	v_mfma_f32_16x16x32_bf16 v[92:95], v[168:171], v[216:219], v[92:95]
	v_mfma_f32_16x16x32_bf16 v[84:87], v[192:195], v[216:219], v[84:87]
	v_mfma_f32_16x16x32_bf16 v[76:79], v[168:171], v[224:227], v[76:79]
	v_mfma_f32_16x16x32_bf16 v[68:71], v[192:195], v[224:227], v[68:71]
	v_mfma_f32_16x16x32_bf16 v[124:127], v[172:175], v[204:207], v[124:127]
	v_mfma_f32_16x16x32_bf16 v[120:123], v[196:199], v[204:207], v[120:123]
	v_mfma_f32_16x16x32_bf16 v[108:111], v[172:175], v[212:215], v[108:111]
	v_mfma_f32_16x16x32_bf16 v[100:103], v[196:199], v[212:215], v[100:103]
	v_mfma_f32_16x16x32_bf16 v[92:95], v[172:175], v[220:223], v[92:95]
	v_mfma_f32_16x16x32_bf16 v[84:87], v[196:199], v[220:223], v[84:87]
	v_mfma_f32_16x16x32_bf16 v[76:79], v[172:175], v[228:231], v[76:79]
	v_mfma_f32_16x16x32_bf16 v[68:71], v[196:199], v[228:231], v[68:71]
	s_barrier
	s_setprio 0
	s_add_i32 s69, s82, s15
	v_lshl_add_u64 v[140:141], s[76:77], 0, v[152:153]
	s_mov_b32 m0, s69
	ds_read_b128 v[200:203], v145 offset:16384
	ds_read_b128 v[204:207], v145 offset:17408
	ds_read_b128 v[208:211], v145 offset:18432
	ds_read_b128 v[212:215], v145 offset:19456
	ds_read_b128 v[216:219], v145 offset:20480
	ds_read_b128 v[220:223], v145 offset:21504
	ds_read_b128 v[224:227], v145 offset:22528
	ds_read_b128 v[228:231], v145 offset:23552
	global_load_lds_dwordx4 v[140:141], off
	s_add_i32 m0, s69, 0x2000
	s_add_u32 s82, s76, 0x80000
	v_lshl_add_u64 v[150:151], s[76:77], 0, v[128:129]
	s_addc_u32 s83, s77, 0
	s_add_i32 s68, s68, s15
	global_load_lds_dwordx4 v[150:151], off
	v_lshl_add_u64 v[182:183], s[82:83], 0, v[152:153]
	s_mov_b32 m0, s68
	v_lshl_add_u64 v[184:185], s[78:79], 0, v[130:131]
	global_load_lds_dwordx4 v[182:183], off
	v_lshl_add_u64 v[182:183], s[82:83], 0, v[128:129]
	s_add_i32 m0, s68, 0x2000
	s_nop 0
	global_load_lds_dwordx4 v[182:183], off
	v_lshl_add_u64 v[182:183], s[78:79], 0, v[132:133]
	s_mov_b32 m0, s16
	s_nop 0
	global_load_lds_dwordx4 v[182:183], off
	s_mov_b32 m0, s17
	s_nop 0
	global_load_lds_dwordx4 v[184:185], off
	s_waitcnt vmcnt(8)
	s_waitcnt lgkmcnt(0)
	s_setprio 1
	s_barrier
; #define PG8_STAGE(bufoff, gbase, voff) do { _Pragma("unroll") for (int _i = 0; _i < 2; ++_i) \
;         __builtin_amdgcn_global_load_lds((const unsigned*)((const char*)(gbase) + (voff)[_i]), (PG8_LAS unsigned*)(lds + (bufoff) + ldsw + _i * 8192), 16, 0, 0); } while (0)
; #define PG8_LDA(dst, b, h) do { _Pragma("unroll") for (int m = 0; m < 4; ++m) _Pragma("unroll") for (int k = 0; k < 2; ++k) dst[m][k] = *(const PG8_LAS bf16x8*)(lds + PG8_SA(b, h) + aoff + m * 2048 + k * 1024); } while (0)
; #define PG8_LDB(dst, b, h) do { _Pragma("unroll") for (int n = 0; n < 2; ++n) _Pragma("unroll") for (int k = 0; k < 2; ++k) dst[n][k] = *(const PG8_LAS bf16x8*)(lds + PG8_SB(b, h) + boff + n * 2048 + k * 1024); } while (0)
; #define PG8_MMA(ai, bj, At, Bt) do { __builtin_amdgcn_s_setprio(1); _Pragma("unroll") for (int m = 0; m < 4; ++m) _Pragma("unroll") for (int n = 0; n < 2; ++n) _Pragma("unroll") for (int k = 0; k < 2; ++k) \
;         acc[ai][bj][m][n] = __builtin_amdgcn_mfma_f32_16x16x32_bf16(Bt[n][k], At[m][k], acc[ai][bj][m][n], 0, 0, 0); __builtin_amdgcn_s_setprio(0); } while (0)
; #define PG8_WAIT_V(n) asm volatile("s_waitcnt vmcnt(" #n ")" ::: "memory")
; #define PG8_WAIT_L(n) asm volatile("s_waitcnt lgkmcnt(" #n ")" ::: "memory")
; #define PG8_BAR __builtin_amdgcn_s_barrier()
; #define PG8_SCHED __builtin_amdgcn_sched_barrier(0)
; template <class Epi, class Sched, bool ALIGN_EPI = false, bool SP2 = false>
; __device__ __forceinline__ void gemm_phase(PG8_LAS unsigned char* lds, const Gemm g, const Sched& S, const Epi& E) {
;     ...
;             PG8_WAIT_V(8); PG8_WAIT_L(0); PG8_BAR; PG8_MMA(1, 0, At, B0); PG8_MMA(1, 1, At, B1); PG8_BAR; PG8_SCHED;
;             PG8_LDB(B0, 1, 0); PG8_LDB(B1, 1, 1); PG8_SCHED; PG8_LDA(At, 1, 0); PG8_STAGE(PG8_SA(0, 1), a2 + hstep, voffA);
;             PG8_WAIT_V(8); PG8_WAIT_L(0); PG8_BAR; PG8_MMA(0, 0, At, B0); PG8_MMA(0, 1, At, B1); PG8_BAR; PG8_SCHED;
;             PG8_LDA(At, 1, 1); PG8_STAGE(PG8_SB(1, 0), b3, voffB); PG8_STAGE(PG8_SB(1, 1), b3 + hstep, voffB); PG8_STAGE(PG8_SA(1, 0), a3, voffA);
	v_mfma_f32_16x16x32_bf16 v[56:59], v[146:149], v[200:203], v[56:59]
	v_mfma_f32_16x16x32_bf16 v[48:51], v[160:163], v[200:203], v[48:51]
	v_mfma_f32_16x16x32_bf16 v[40:43], v[146:149], v[208:211], v[40:43]
	v_mfma_f32_16x16x32_bf16 v[32:35], v[160:163], v[208:211], v[32:35]
	v_mfma_f32_16x16x32_bf16 v[24:27], v[146:149], v[216:219], v[24:27]
	v_mfma_f32_16x16x32_bf16 v[16:19], v[160:163], v[216:219], v[16:19]
	v_mfma_f32_16x16x32_bf16 v[8:11], v[146:149], v[224:227], v[8:11]
	v_mfma_f32_16x16x32_bf16 v[4:7], v[160:163], v[224:227], v[4:7]
	v_mfma_f32_16x16x32_bf16 v[56:59], v[156:159], v[204:207], v[56:59]
	v_mfma_f32_16x16x32_bf16 v[48:51], v[164:167], v[204:207], v[48:51]
	v_mfma_f32_16x16x32_bf16 v[40:43], v[156:159], v[212:215], v[40:43]
	v_mfma_f32_16x16x32_bf16 v[32:35], v[164:167], v[212:215], v[32:35]
	v_mfma_f32_16x16x32_bf16 v[24:27], v[156:159], v[220:223], v[24:27]
	v_mfma_f32_16x16x32_bf16 v[16:19], v[164:167], v[220:223], v[16:19]
	v_mfma_f32_16x16x32_bf16 v[8:11], v[156:159], v[228:231], v[8:11]
	v_mfma_f32_16x16x32_bf16 v[4:7], v[164:167], v[228:231], v[4:7]
	v_mfma_f32_16x16x32_bf16 v[60:63], v[168:171], v[200:203], v[60:63]
	v_mfma_f32_16x16x32_bf16 v[52:55], v[192:195], v[200:203], v[52:55]
	v_mfma_f32_16x16x32_bf16 v[44:47], v[168:171], v[208:211], v[44:47]
	v_mfma_f32_16x16x32_bf16 v[36:39], v[192:195], v[208:211], v[36:39]
	v_mfma_f32_16x16x32_bf16 v[28:31], v[168:171], v[216:219], v[28:31]
	v_mfma_f32_16x16x32_bf16 v[20:23], v[192:195], v[216:219], v[20:23]
	v_mfma_f32_16x16x32_bf16 v[12:15], v[168:171], v[224:227], v[12:15]
	v_mfma_f32_16x16x32_bf16 v[0:3], v[192:195], v[224:227], v[0:3]
	v_mfma_f32_16x16x32_bf16 v[60:63], v[172:175], v[204:207], v[60:63]
	v_mfma_f32_16x16x32_bf16 v[52:55], v[196:199], v[204:207], v[52:55]
	v_mfma_f32_16x16x32_bf16 v[44:47], v[172:175], v[212:215], v[44:47]
	v_mfma_f32_16x16x32_bf16 v[36:39], v[196:199], v[212:215], v[36:39]
	v_mfma_f32_16x16x32_bf16 v[28:31], v[172:175], v[220:223], v[28:31]
	v_mfma_f32_16x16x32_bf16 v[20:23], v[196:199], v[220:223], v[20:23]
	v_mfma_f32_16x16x32_bf16 v[12:15], v[172:175], v[228:231], v[12:15]
	v_mfma_f32_16x16x32_bf16 v[0:3], v[196:199], v[228:231], v[0:3]
	s_barrier
	s_setprio 0
	v_add_u32_e32 v155, s93, v143
	s_add_i32 s68, 0, 0x1c000
	ds_read_b128 v[146:149], v155
	ds_read_b128 v[156:159], v155 offset:1024
	ds_read_b128 v[160:163], v155 offset:2048
	ds_read_b128 v[164:167], v155 offset:3072
	v_add_u32_e32 v155, s68, v143
	ds_read_b128 v[168:171], v155
	ds_read_b128 v[172:175], v155 offset:1024
	ds_read_b128 v[192:195], v155 offset:2048
	ds_read_b128 v[196:199], v155 offset:3072
	s_add_u32 s78, s78, 0x80000
	s_addc_u32 s79, s79, 0
	s_mov_b32 m0, s22
	v_lshl_add_u64 v[188:189], s[78:79], 0, v[132:133]
	ds_read_b128 v[200:203], v145 offset:32768
	ds_read_b128 v[204:207], v145 offset:33792
	ds_read_b128 v[208:211], v145 offset:34816
	ds_read_b128 v[212:215], v145 offset:35840
	ds_read_b128 v[216:219], v145 offset:36864
	ds_read_b128 v[220:223], v145 offset:37888
	ds_read_b128 v[224:227], v145 offset:38912
	ds_read_b128 v[228:231], v145 offset:39936
	global_load_lds_dwordx4 v[188:189], off
	v_lshl_add_u64 v[188:189], s[78:79], 0, v[130:131]
	s_mov_b32 m0, s23
	s_nop 0
	global_load_lds_dwordx4 v[188:189], off
	s_waitcnt vmcnt(8)
	s_waitcnt lgkmcnt(0)
	s_setprio 1
	s_barrier
	v_mfma_f32_16x16x32_bf16 v[116:119], v[146:149], v[200:203], v[116:119]
	v_mfma_f32_16x16x32_bf16 v[112:115], v[160:163], v[200:203], v[112:115]
	v_mfma_f32_16x16x32_bf16 v[104:107], v[146:149], v[208:211], v[104:107]
	v_mfma_f32_16x16x32_bf16 v[96:99], v[160:163], v[208:211], v[96:99]
	v_mfma_f32_16x16x32_bf16 v[88:91], v[146:149], v[216:219], v[88:91]
	v_mfma_f32_16x16x32_bf16 v[80:83], v[160:163], v[216:219], v[80:83]
	v_mfma_f32_16x16x32_bf16 v[72:75], v[146:149], v[224:227], v[72:75]
	v_mfma_f32_16x16x32_bf16 v[64:67], v[160:163], v[224:227], v[64:67]
	v_mfma_f32_16x16x32_bf16 v[116:119], v[156:159], v[204:207], v[116:119]
	v_mfma_f32_16x16x32_bf16 v[112:115], v[164:167], v[204:207], v[112:115]
	v_mfma_f32_16x16x32_bf16 v[104:107], v[156:159], v[212:215], v[104:107]
	v_mfma_f32_16x16x32_bf16 v[96:99], v[164:167], v[212:215], v[96:99]
	v_mfma_f32_16x16x32_bf16 v[88:91], v[156:159], v[220:223], v[88:91]
	v_mfma_f32_16x16x32_bf16 v[80:83], v[164:167], v[220:223], v[80:83]
	v_mfma_f32_16x16x32_bf16 v[72:75], v[156:159], v[228:231], v[72:75]
	v_mfma_f32_16x16x32_bf16 v[64:67], v[164:167], v[228:231], v[64:67]
	v_mfma_f32_16x16x32_bf16 v[124:127], v[168:171], v[200:203], v[124:127]
	v_mfma_f32_16x16x32_bf16 v[120:123], v[192:195], v[200:203], v[120:123]
	v_mfma_f32_16x16x32_bf16 v[108:111], v[168:171], v[208:211], v[108:111]
	v_mfma_f32_16x16x32_bf16 v[100:103], v[192:195], v[208:211], v[100:103]
	v_mfma_f32_16x16x32_bf16 v[92:95], v[168:171], v[216:219], v[92:95]
	v_mfma_f32_16x16x32_bf16 v[84:87], v[192:195], v[216:219], v[84:87]
	v_mfma_f32_16x16x32_bf16 v[76:79], v[168:171], v[224:227], v[76:79]
	v_mfma_f32_16x16x32_bf16 v[68:71], v[192:195], v[224:227], v[68:71]
	v_mfma_f32_16x16x32_bf16 v[124:127], v[172:175], v[204:207], v[124:127]
	v_mfma_f32_16x16x32_bf16 v[120:123], v[196:199], v[204:207], v[120:123]
	v_mfma_f32_16x16x32_bf16 v[108:111], v[172:175], v[212:215], v[108:111]
	v_mfma_f32_16x16x32_bf16 v[100:103], v[196:199], v[212:215], v[100:103]
	v_mfma_f32_16x16x32_bf16 v[92:95], v[172:175], v[220:223], v[92:95]
	v_mfma_f32_16x16x32_bf16 v[84:87], v[196:199], v[220:223], v[84:87]
	v_mfma_f32_16x16x32_bf16 v[76:79], v[172:175], v[228:231], v[76:79]
	v_mfma_f32_16x16x32_bf16 v[68:71], v[196:199], v[228:231], v[68:71]
	s_barrier
; #define PG8_STAGE(bufoff, gbase, voff) do { _Pragma("unroll") for (int _i = 0; _i < 2; ++_i) \
;         __builtin_amdgcn_global_load_lds((const unsigned*)((const char*)(gbase) + (voff)[_i]), (PG8_LAS unsigned*)(lds + (bufoff) + ldsw + _i * 8192), 16, 0, 0); } while (0)
; #define PG8_LDA(dst, b, h) do { _Pragma("unroll") for (int m = 0; m < 4; ++m) _Pragma("unroll") for (int k = 0; k < 2; ++k) dst[m][k] = *(const PG8_LAS bf16x8*)(lds + PG8_SA(b, h) + aoff + m * 2048 + k * 1024); } while (0)
; #define PG8_MMA(ai, bj, At, Bt) do { __builtin_amdgcn_s_setprio(1); _Pragma("unroll") for (int m = 0; m < 4; ++m) _Pragma("unroll") for (int n = 0; n < 2; ++n) _Pragma("unroll") for (int k = 0; k < 2; ++k) \
;         acc[ai][bj][m][n] = __builtin_amdgcn_mfma_f32_16x16x32_bf16(Bt[n][k], At[m][k], acc[ai][bj][m][n], 0, 0, 0); __builtin_amdgcn_s_setprio(0); } while (0)
; #define PG8_WAIT_V(n) asm volatile("s_waitcnt vmcnt(" #n ")" ::: "memory")
; #define PG8_WAIT_L(n) asm volatile("s_waitcnt lgkmcnt(" #n ")" ::: "memory")
; #define PG8_BAR __builtin_amdgcn_s_barrier()
; #define PG8_SCHED __builtin_amdgcn_sched_barrier(0)
; template <class Epi, class Sched, bool ALIGN_EPI = false, bool SP2 = false>
; __device__ __forceinline__ void gemm_phase(PG8_LAS unsigned char* lds, const Gemm g, const Sched& S, const Epi& E) {
;     ...
;         for (int t = 0; t < nt; t += 2) {
;             const bool last = (t == nt - 2);
;     ...
;             PG8_LDA(At, 1, 1); PG8_STAGE(PG8_SB(1, 0), b3, voffB); PG8_STAGE(PG8_SB(1, 1), b3 + hstep, voffB); PG8_STAGE(PG8_SA(1, 0), a3, voffA);
;             PG8_WAIT_V(8); PG8_WAIT_L(0); PG8_BAR; PG8_MMA(1, 0, At, B0); PG8_MMA(1, 1, At, B1); PG8_BAR; PG8_SCHED;
	s_setprio 0
	s_add_i32 s69, s93, s15
	v_lshl_add_u64 v[140:141], v[140:141], 0, s[18:19]
	s_mov_b32 m0, s69
	ds_read_b128 v[200:203], v145 offset:49152
	ds_read_b128 v[204:207], v145 offset:50176
	ds_read_b128 v[208:211], v145 offset:51200
	ds_read_b128 v[212:215], v145 offset:52224
	ds_read_b128 v[216:219], v145 offset:53248
	ds_read_b128 v[220:223], v145 offset:54272
	ds_read_b128 v[224:227], v145 offset:55296
	ds_read_b128 v[228:231], v145 offset:56320
	global_load_lds_dwordx4 v[140:141], off
	s_add_i32 m0, s69, 0x2000
	s_add_u32 s76, s76, 0x80080
	v_lshl_add_u64 v[140:141], v[150:151], 0, s[18:19]
	s_addc_u32 s77, s77, 0
	s_add_i32 s68, s68, s15
	global_load_lds_dwordx4 v[140:141], off
	v_lshl_add_u64 v[140:141], s[76:77], 0, v[152:153]
	s_mov_b32 m0, s68
	s_nop 0
	global_load_lds_dwordx4 v[140:141], off
	v_lshl_add_u64 v[140:141], s[76:77], 0, v[128:129]
	s_add_i32 m0, s68, 0x2000
	s_nop 0
	global_load_lds_dwordx4 v[140:141], off
	v_lshl_add_u64 v[140:141], v[182:183], 0, s[18:19]
	s_mov_b32 m0, s26
	s_nop 0
	global_load_lds_dwordx4 v[140:141], off
	v_lshl_add_u64 v[140:141], v[184:185], 0, s[18:19]
	s_mov_b32 m0, s34
	s_nop 0
	global_load_lds_dwordx4 v[140:141], off
	s_waitcnt vmcnt(8)
	s_waitcnt lgkmcnt(0)
	s_setprio 1
	s_barrier
	v_mfma_f32_16x16x32_bf16 v[56:59], v[146:149], v[200:203], v[56:59]
	v_mfma_f32_16x16x32_bf16 v[48:51], v[160:163], v[200:203], v[48:51]
	v_mfma_f32_16x16x32_bf16 v[40:43], v[146:149], v[208:211], v[40:43]
	v_mfma_f32_16x16x32_bf16 v[32:35], v[160:163], v[208:211], v[32:35]
	v_mfma_f32_16x16x32_bf16 v[24:27], v[146:149], v[216:219], v[24:27]
	v_mfma_f32_16x16x32_bf16 v[16:19], v[160:163], v[216:219], v[16:19]
	v_mfma_f32_16x16x32_bf16 v[8:11], v[146:149], v[224:227], v[8:11]
	v_mfma_f32_16x16x32_bf16 v[4:7], v[160:163], v[224:227], v[4:7]
	v_mfma_f32_16x16x32_bf16 v[56:59], v[156:159], v[204:207], v[56:59]
	v_mfma_f32_16x16x32_bf16 v[48:51], v[164:167], v[204:207], v[48:51]
	v_mfma_f32_16x16x32_bf16 v[40:43], v[156:159], v[212:215], v[40:43]
	v_mfma_f32_16x16x32_bf16 v[32:35], v[164:167], v[212:215], v[32:35]
	v_mfma_f32_16x16x32_bf16 v[24:27], v[156:159], v[220:223], v[24:27]
	v_mfma_f32_16x16x32_bf16 v[16:19], v[164:167], v[220:223], v[16:19]
	v_mfma_f32_16x16x32_bf16 v[8:11], v[156:159], v[228:231], v[8:11]
	v_mfma_f32_16x16x32_bf16 v[4:7], v[164:167], v[228:231], v[4:7]
	v_mfma_f32_16x16x32_bf16 v[60:63], v[168:171], v[200:203], v[60:63]
	v_mfma_f32_16x16x32_bf16 v[52:55], v[192:195], v[200:203], v[52:55]
	v_mfma_f32_16x16x32_bf16 v[44:47], v[168:171], v[208:211], v[44:47]
	v_mfma_f32_16x16x32_bf16 v[36:39], v[192:195], v[208:211], v[36:39]
	v_mfma_f32_16x16x32_bf16 v[28:31], v[168:171], v[216:219], v[28:31]
	v_mfma_f32_16x16x32_bf16 v[20:23], v[192:195], v[216:219], v[20:23]
	v_mfma_f32_16x16x32_bf16 v[12:15], v[168:171], v[224:227], v[12:15]
	v_mfma_f32_16x16x32_bf16 v[0:3], v[192:195], v[224:227], v[0:3]
	v_mfma_f32_16x16x32_bf16 v[60:63], v[172:175], v[204:207], v[60:63]
	v_mfma_f32_16x16x32_bf16 v[52:55], v[196:199], v[204:207], v[52:55]
	v_mfma_f32_16x16x32_bf16 v[44:47], v[172:175], v[212:215], v[44:47]
	v_mfma_f32_16x16x32_bf16 v[36:39], v[196:199], v[212:215], v[36:39]
	v_mfma_f32_16x16x32_bf16 v[28:31], v[172:175], v[220:223], v[28:31]
	v_mfma_f32_16x16x32_bf16 v[20:23], v[196:199], v[220:223], v[20:23]
	v_mfma_f32_16x16x32_bf16 v[12:15], v[172:175], v[228:231], v[12:15]
	v_mfma_f32_16x16x32_bf16 v[0:3], v[196:199], v[228:231], v[0:3]
	s_add_i32 s81, s81, 2
	s_add_u32 s74, s74, 0x100
	s_addc_u32 s75, s75, 0
	s_add_u32 s71, s71, 0x100
	s_addc_u32 s80, s80, 0
	s_cmp_gt_u32 s81, 29
	s_cbranch_scc1 .Llastbar_331
	s_barrier
	s_setprio 0
	s_branch .LBB0_331

; #define PG8_STAGE(bufoff, gbase, voff) do { _Pragma("unroll") for (int _i = 0; _i < 2; ++_i) \
;         __builtin_amdgcn_global_load_lds((const unsigned*)((const char*)(gbase) + (voff)[_i]), (PG8_LAS unsigned*)(lds + (bufoff) + ldsw + _i * 8192), 16, 0, 0); } while (0)
; #define PG8_LDA(dst, b, h) do { _Pragma("unroll") for (int m = 0; m < 4; ++m) _Pragma("unroll") for (int k = 0; k < 2; ++k) dst[m][k] = *(const PG8_LAS bf16x8*)(lds + PG8_SA(b, h) + aoff + m * 2048 + k * 1024); } while (0)
; #define PG8_LDB(dst, b, h) do { _Pragma("unroll") for (int n = 0; n < 2; ++n) _Pragma("unroll") for (int k = 0; k < 2; ++k) dst[n][k] = *(const PG8_LAS bf16x8*)(lds + PG8_SB(b, h) + boff + n * 2048 + k * 1024); } while (0)
; #define PG8_MMA(ai, bj, At, Bt) do { __builtin_amdgcn_s_setprio(1); _Pragma("unroll") for (int m = 0; m < 4; ++m) _Pragma("unroll") for (int n = 0; n < 2; ++n) _Pragma("unroll") for (int k = 0; k < 2; ++k) \
;         acc[ai][bj][m][n] = __builtin_amdgcn_mfma_f32_16x16x32_bf16(Bt[n][k], At[m][k], acc[ai][bj][m][n], 0, 0, 0); __builtin_amdgcn_s_setprio(0); } while (0)
; #define PG8_WAIT_V(n) asm volatile("s_waitcnt vmcnt(" #n ")" ::: "memory")
; #define PG8_WAIT_L(n) asm volatile("s_waitcnt lgkmcnt(" #n ")" ::: "memory")
; #define PG8_BAR __builtin_amdgcn_s_barrier()
; #define PG8_SCHED __builtin_amdgcn_sched_barrier(0)
; template <class Epi, class Sched, bool ALIGN_EPI = false, bool SP2 = false>
; __device__ __forceinline__ void gemm_phase(PG8_LAS unsigned char* lds, const Gemm g, const Sched& S, const Epi& E) {
;     ...
;             PG8_LDB(B0, 0, 0); PG8_LDB(B1, 0, 1); PG8_SCHED; PG8_LDA(At, 0, 0); PG8_STAGE(PG8_SA(1, 1), a1 + hstep, voffA);
;             PG8_WAIT_V(8); PG8_WAIT_L(0); PG8_BAR; PG8_MMA(0, 0, At, B0); PG8_MMA(0, 1, At, B1); PG8_BAR; PG8_SCHED;
;             PG8_LDA(At, 0, 1); PG8_STAGE(PG8_SB(0, 0), b2, voffB); PG8_STAGE(PG8_SB(0, 1), b2 + hstep, voffB); PG8_STAGE(PG8_SA(0, 0), a2, voffA);
;             PG8_WAIT_V(8); PG8_WAIT_L(0); PG8_BAR; PG8_MMA(1, 0, At, B0); PG8_MMA(1, 1, At, B1); PG8_BAR; PG8_SCHED;
.LBB0_354:
	s_add_u32 s68, s48, 0xfff80080
	s_addc_u32 s69, s49, -1
	s_add_i32 s78, 0, 0x10000
	s_cmp_eq_u32 s71, 28
	s_cselect_b32 s77, s41, s69
	s_cselect_b32 s76, s55, s68
	v_add_u32_e32 v150, s78, v139
	s_cselect_b32 s75, s39, s63
	s_cselect_b32 s74, s58, s59
	s_add_i32 s68, 0, 0x14000
	ds_read_b128 v[142:145], v150
	ds_read_b128 v[146:149], v150 offset:1024
	ds_read_b128 v[156:159], v150 offset:2048
	ds_read_b128 v[160:163], v150 offset:3072
	v_add_u32_e32 v150, s68, v139
	ds_read_b128 v[164:167], v150
	ds_read_b128 v[168:171], v150 offset:1024
	ds_read_b128 v[172:175], v150 offset:2048
	ds_read_b128 v[192:195], v150 offset:3072
	v_lshl_add_u64 v[150:151], s[48:49], 0, v[134:135]
	s_add_i32 m0, s16, 0xc000
	ds_read_b128 v[196:199], v141
	ds_read_b128 v[200:203], v141 offset:1024
	ds_read_b128 v[204:207], v141 offset:2048
	ds_read_b128 v[208:211], v141 offset:3072
	ds_read_b128 v[212:215], v141 offset:4096
	ds_read_b128 v[216:219], v141 offset:5120
	ds_read_b128 v[220:223], v141 offset:6144
	ds_read_b128 v[224:227], v141 offset:7168
	global_load_lds_dwordx4 v[150:151], off
	v_lshl_add_u64 v[150:151], s[48:49], 0, v[136:137]
	s_add_i32 m0, s16, 0xe000
	s_nop 0
	global_load_lds_dwordx4 v[150:151], off
	s_waitcnt vmcnt(8)
	s_waitcnt lgkmcnt(0)
	s_setprio 1
	s_barrier
	v_mfma_f32_16x16x32_bf16 v[124:127], v[142:145], v[196:199], v[124:127]
	v_mfma_f32_16x16x32_bf16 v[120:123], v[156:159], v[196:199], v[120:123]
	v_mfma_f32_16x16x32_bf16 v[116:119], v[142:145], v[204:207], v[116:119]
	v_mfma_f32_16x16x32_bf16 v[108:111], v[156:159], v[204:207], v[108:111]
	v_mfma_f32_16x16x32_bf16 v[100:103], v[142:145], v[212:215], v[100:103]
	v_mfma_f32_16x16x32_bf16 v[92:95], v[156:159], v[212:215], v[92:95]
	v_mfma_f32_16x16x32_bf16 v[84:87], v[142:145], v[220:223], v[84:87]
	v_mfma_f32_16x16x32_bf16 v[76:79], v[156:159], v[220:223], v[76:79]
	v_mfma_f32_16x16x32_bf16 v[124:127], v[146:149], v[200:203], v[124:127]
	v_mfma_f32_16x16x32_bf16 v[120:123], v[160:163], v[200:203], v[120:123]
	v_mfma_f32_16x16x32_bf16 v[116:119], v[146:149], v[208:211], v[116:119]
	v_mfma_f32_16x16x32_bf16 v[108:111], v[160:163], v[208:211], v[108:111]
	v_mfma_f32_16x16x32_bf16 v[100:103], v[146:149], v[216:219], v[100:103]
	v_mfma_f32_16x16x32_bf16 v[92:95], v[160:163], v[216:219], v[92:95]
	v_mfma_f32_16x16x32_bf16 v[84:87], v[146:149], v[224:227], v[84:87]
	v_mfma_f32_16x16x32_bf16 v[76:79], v[160:163], v[224:227], v[76:79]
	v_mfma_f32_16x16x32_bf16 v[112:115], v[164:167], v[196:199], v[112:115]
	v_mfma_f32_16x16x32_bf16 v[104:107], v[172:175], v[196:199], v[104:107]
	v_mfma_f32_16x16x32_bf16 v[96:99], v[164:167], v[204:207], v[96:99]
	v_mfma_f32_16x16x32_bf16 v[88:91], v[172:175], v[204:207], v[88:91]
	v_mfma_f32_16x16x32_bf16 v[80:83], v[164:167], v[212:215], v[80:83]
	v_mfma_f32_16x16x32_bf16 v[72:75], v[172:175], v[212:215], v[72:75]
	v_mfma_f32_16x16x32_bf16 v[68:71], v[164:167], v[220:223], v[68:71]
	v_mfma_f32_16x16x32_bf16 v[64:67], v[172:175], v[220:223], v[64:67]
	v_mfma_f32_16x16x32_bf16 v[112:115], v[168:171], v[200:203], v[112:115]
	v_mfma_f32_16x16x32_bf16 v[104:107], v[192:195], v[200:203], v[104:107]
	v_mfma_f32_16x16x32_bf16 v[96:99], v[168:171], v[208:211], v[96:99]
	v_mfma_f32_16x16x32_bf16 v[88:91], v[192:195], v[208:211], v[88:91]
	v_mfma_f32_16x16x32_bf16 v[80:83], v[168:171], v[216:219], v[80:83]
	v_mfma_f32_16x16x32_bf16 v[72:75], v[192:195], v[216:219], v[72:75]
	v_mfma_f32_16x16x32_bf16 v[68:71], v[168:171], v[224:227], v[68:71]
	v_mfma_f32_16x16x32_bf16 v[64:67], v[192:195], v[224:227], v[64:67]
	s_barrier
	s_setprio 0
	s_add_i32 s69, s78, s0
	v_lshl_add_u64 v[150:151], s[74:75], 0, v[152:153]
	s_mov_b32 m0, s69
	ds_read_b128 v[196:199], v141 offset:16384
	ds_read_b128 v[200:203], v141 offset:17408
	ds_read_b128 v[204:207], v141 offset:18432
	ds_read_b128 v[208:211], v141 offset:19456
	ds_read_b128 v[212:215], v141 offset:20480
	ds_read_b128 v[216:219], v141 offset:21504
	ds_read_b128 v[220:223], v141 offset:22528
	ds_read_b128 v[224:227], v141 offset:23552
	global_load_lds_dwordx4 v[150:151], off
	s_add_i32 m0, s69, 0x2000
	s_add_u32 s78, s74, 0x80000
	v_lshl_add_u64 v[182:183], s[74:75], 0, v[132:133]
	s_addc_u32 s79, s75, 0
	s_add_i32 s68, s68, s0
	global_load_lds_dwordx4 v[182:183], off
	v_lshl_add_u64 v[184:185], s[78:79], 0, v[152:153]
	s_mov_b32 m0, s68
	v_lshl_add_u64 v[188:189], s[76:77], 0, v[130:131]
	global_load_lds_dwordx4 v[184:185], off
	v_lshl_add_u64 v[184:185], s[78:79], 0, v[132:133]
	s_add_i32 m0, s68, 0x2000
	s_nop 0
	global_load_lds_dwordx4 v[184:185], off
	v_lshl_add_u64 v[184:185], s[76:77], 0, v[128:129]
	s_mov_b32 m0, s16
	s_nop 0
	global_load_lds_dwordx4 v[184:185], off
	s_mov_b32 m0, s17
	s_nop 0
	global_load_lds_dwordx4 v[188:189], off
	s_waitcnt vmcnt(8)
	s_waitcnt lgkmcnt(0)
	s_setprio 1
	s_barrier
; #define PG8_STAGE(bufoff, gbase, voff) do { _Pragma("unroll") for (int _i = 0; _i < 2; ++_i) \
;         __builtin_amdgcn_global_load_lds((const unsigned*)((const char*)(gbase) + (voff)[_i]), (PG8_LAS unsigned*)(lds + (bufoff) + ldsw + _i * 8192), 16, 0, 0); } while (0)
; #define PG8_LDA(dst, b, h) do { _Pragma("unroll") for (int m = 0; m < 4; ++m) _Pragma("unroll") for (int k = 0; k < 2; ++k) dst[m][k] = *(const PG8_LAS bf16x8*)(lds + PG8_SA(b, h) + aoff + m * 2048 + k * 1024); } while (0)
; #define PG8_LDB(dst, b, h) do { _Pragma("unroll") for (int n = 0; n < 2; ++n) _Pragma("unroll") for (int k = 0; k < 2; ++k) dst[n][k] = *(const PG8_LAS bf16x8*)(lds + PG8_SB(b, h) + boff + n * 2048 + k * 1024); } while (0)
; #define PG8_MMA(ai, bj, At, Bt) do { __builtin_amdgcn_s_setprio(1); _Pragma("unroll") for (int m = 0; m < 4; ++m) _Pragma("unroll") for (int n = 0; n < 2; ++n) _Pragma("unroll") for (int k = 0; k < 2; ++k) \
;         acc[ai][bj][m][n] = __builtin_amdgcn_mfma_f32_16x16x32_bf16(Bt[n][k], At[m][k], acc[ai][bj][m][n], 0, 0, 0); __builtin_amdgcn_s_setprio(0); } while (0)
; #define PG8_WAIT_V(n) asm volatile("s_waitcnt vmcnt(" #n ")" ::: "memory")
; #define PG8_WAIT_L(n) asm volatile("s_waitcnt lgkmcnt(" #n ")" ::: "memory")
; #define PG8_BAR __builtin_amdgcn_s_barrier()
; #define PG8_SCHED __builtin_amdgcn_sched_barrier(0)
; template <class Epi, class Sched, bool ALIGN_EPI = false, bool SP2 = false>
; __device__ __forceinline__ void gemm_phase(PG8_LAS unsigned char* lds, const Gemm g, const Sched& S, const Epi& E) {
;     ...
;             PG8_WAIT_V(8); PG8_WAIT_L(0); PG8_BAR; PG8_MMA(1, 0, At, B0); PG8_MMA(1, 1, At, B1); PG8_BAR; PG8_SCHED;
;             PG8_LDB(B0, 1, 0); PG8_LDB(B1, 1, 1); PG8_SCHED; PG8_LDA(At, 1, 0); PG8_STAGE(PG8_SA(0, 1), a2 + hstep, voffA);
;             PG8_WAIT_V(8); PG8_WAIT_L(0); PG8_BAR; PG8_MMA(0, 0, At, B0); PG8_MMA(0, 1, At, B1); PG8_BAR; PG8_SCHED;
;             PG8_LDA(At, 1, 1); PG8_STAGE(PG8_SB(1, 0), b3, voffB); PG8_STAGE(PG8_SB(1, 1), b3 + hstep, voffB); PG8_STAGE(PG8_SA(1, 0), a3, voffA);
	v_mfma_f32_16x16x32_bf16 v[60:63], v[142:145], v[196:199], v[60:63]
	v_mfma_f32_16x16x32_bf16 v[56:59], v[156:159], v[196:199], v[56:59]
	v_mfma_f32_16x16x32_bf16 v[52:55], v[142:145], v[204:207], v[52:55]
	v_mfma_f32_16x16x32_bf16 v[44:47], v[156:159], v[204:207], v[44:47]
	v_mfma_f32_16x16x32_bf16 v[36:39], v[142:145], v[212:215], v[36:39]
	v_mfma_f32_16x16x32_bf16 v[28:31], v[156:159], v[212:215], v[28:31]
	v_mfma_f32_16x16x32_bf16 v[20:23], v[142:145], v[220:223], v[20:23]
	v_mfma_f32_16x16x32_bf16 v[12:15], v[156:159], v[220:223], v[12:15]
	v_mfma_f32_16x16x32_bf16 v[60:63], v[146:149], v[200:203], v[60:63]
	v_mfma_f32_16x16x32_bf16 v[56:59], v[160:163], v[200:203], v[56:59]
	v_mfma_f32_16x16x32_bf16 v[52:55], v[146:149], v[208:211], v[52:55]
	v_mfma_f32_16x16x32_bf16 v[44:47], v[160:163], v[208:211], v[44:47]
	v_mfma_f32_16x16x32_bf16 v[36:39], v[146:149], v[216:219], v[36:39]
	v_mfma_f32_16x16x32_bf16 v[28:31], v[160:163], v[216:219], v[28:31]
	v_mfma_f32_16x16x32_bf16 v[20:23], v[146:149], v[224:227], v[20:23]
	v_mfma_f32_16x16x32_bf16 v[12:15], v[160:163], v[224:227], v[12:15]
	v_mfma_f32_16x16x32_bf16 v[48:51], v[164:167], v[196:199], v[48:51]
	v_mfma_f32_16x16x32_bf16 v[40:43], v[172:175], v[196:199], v[40:43]
	v_mfma_f32_16x16x32_bf16 v[32:35], v[164:167], v[204:207], v[32:35]
	v_mfma_f32_16x16x32_bf16 v[24:27], v[172:175], v[204:207], v[24:27]
	v_mfma_f32_16x16x32_bf16 v[16:19], v[164:167], v[212:215], v[16:19]
	v_mfma_f32_16x16x32_bf16 v[8:11], v[172:175], v[212:215], v[8:11]
	v_mfma_f32_16x16x32_bf16 v[4:7], v[164:167], v[220:223], v[4:7]
	v_mfma_f32_16x16x32_bf16 v[0:3], v[172:175], v[220:223], v[0:3]
	v_mfma_f32_16x16x32_bf16 v[48:51], v[168:171], v[200:203], v[48:51]
	v_mfma_f32_16x16x32_bf16 v[40:43], v[192:195], v[200:203], v[40:43]
	v_mfma_f32_16x16x32_bf16 v[32:35], v[168:171], v[208:211], v[32:35]
	v_mfma_f32_16x16x32_bf16 v[24:27], v[192:195], v[208:211], v[24:27]
	v_mfma_f32_16x16x32_bf16 v[16:19], v[168:171], v[216:219], v[16:19]
	v_mfma_f32_16x16x32_bf16 v[8:11], v[192:195], v[216:219], v[8:11]
	v_mfma_f32_16x16x32_bf16 v[4:7], v[168:171], v[224:227], v[4:7]
	v_mfma_f32_16x16x32_bf16 v[0:3], v[192:195], v[224:227], v[0:3]
	s_barrier
	s_setprio 0
	v_add_u32_e32 v155, s93, v139
	s_add_i32 s68, 0, 0x1c000
	ds_read_b128 v[142:145], v155
	ds_read_b128 v[146:149], v155 offset:1024
	ds_read_b128 v[156:159], v155 offset:2048
	ds_read_b128 v[160:163], v155 offset:3072
	v_add_u32_e32 v155, s68, v139
	ds_read_b128 v[164:167], v155
	ds_read_b128 v[168:171], v155 offset:1024
	ds_read_b128 v[172:175], v155 offset:2048
	ds_read_b128 v[192:195], v155 offset:3072
	s_add_u32 s76, s76, 0x80000
	s_addc_u32 s77, s77, 0
	s_mov_b32 m0, s22
	v_lshl_add_u64 v[190:191], s[76:77], 0, v[128:129]
	ds_read_b128 v[196:199], v141 offset:32768
	ds_read_b128 v[200:203], v141 offset:33792
	ds_read_b128 v[204:207], v141 offset:34816
	ds_read_b128 v[208:211], v141 offset:35840
	ds_read_b128 v[212:215], v141 offset:36864
	ds_read_b128 v[216:219], v141 offset:37888
	ds_read_b128 v[220:223], v141 offset:38912
	ds_read_b128 v[224:227], v141 offset:39936
	global_load_lds_dwordx4 v[190:191], off
	v_lshl_add_u64 v[190:191], s[76:77], 0, v[130:131]
	s_mov_b32 m0, s23
	s_nop 0
	global_load_lds_dwordx4 v[190:191], off
	s_waitcnt vmcnt(8)
	s_waitcnt lgkmcnt(0)
	s_setprio 1
	s_barrier
	v_mfma_f32_16x16x32_bf16 v[124:127], v[142:145], v[196:199], v[124:127]
	v_mfma_f32_16x16x32_bf16 v[120:123], v[156:159], v[196:199], v[120:123]
	v_mfma_f32_16x16x32_bf16 v[116:119], v[142:145], v[204:207], v[116:119]
	v_mfma_f32_16x16x32_bf16 v[108:111], v[156:159], v[204:207], v[108:111]
	v_mfma_f32_16x16x32_bf16 v[100:103], v[142:145], v[212:215], v[100:103]
	v_mfma_f32_16x16x32_bf16 v[92:95], v[156:159], v[212:215], v[92:95]
	v_mfma_f32_16x16x32_bf16 v[84:87], v[142:145], v[220:223], v[84:87]
	v_mfma_f32_16x16x32_bf16 v[76:79], v[156:159], v[220:223], v[76:79]
	v_mfma_f32_16x16x32_bf16 v[124:127], v[146:149], v[200:203], v[124:127]
	v_mfma_f32_16x16x32_bf16 v[120:123], v[160:163], v[200:203], v[120:123]
	v_mfma_f32_16x16x32_bf16 v[116:119], v[146:149], v[208:211], v[116:119]
	v_mfma_f32_16x16x32_bf16 v[108:111], v[160:163], v[208:211], v[108:111]
	v_mfma_f32_16x16x32_bf16 v[100:103], v[146:149], v[216:219], v[100:103]
	v_mfma_f32_16x16x32_bf16 v[92:95], v[160:163], v[216:219], v[92:95]
	v_mfma_f32_16x16x32_bf16 v[84:87], v[146:149], v[224:227], v[84:87]
	v_mfma_f32_16x16x32_bf16 v[76:79], v[160:163], v[224:227], v[76:79]
	v_mfma_f32_16x16x32_bf16 v[112:115], v[164:167], v[196:199], v[112:115]
	v_mfma_f32_16x16x32_bf16 v[104:107], v[172:175], v[196:199], v[104:107]
	v_mfma_f32_16x16x32_bf16 v[96:99], v[164:167], v[204:207], v[96:99]
	v_mfma_f32_16x16x32_bf16 v[88:91], v[172:175], v[204:207], v[88:91]
	v_mfma_f32_16x16x32_bf16 v[80:83], v[164:167], v[212:215], v[80:83]
	v_mfma_f32_16x16x32_bf16 v[72:75], v[172:175], v[212:215], v[72:75]
	v_mfma_f32_16x16x32_bf16 v[68:71], v[164:167], v[220:223], v[68:71]
	v_mfma_f32_16x16x32_bf16 v[64:67], v[172:175], v[220:223], v[64:67]
	v_mfma_f32_16x16x32_bf16 v[112:115], v[168:171], v[200:203], v[112:115]
	v_mfma_f32_16x16x32_bf16 v[104:107], v[192:195], v[200:203], v[104:107]
	v_mfma_f32_16x16x32_bf16 v[96:99], v[168:171], v[208:211], v[96:99]
	v_mfma_f32_16x16x32_bf16 v[88:91], v[192:195], v[208:211], v[88:91]
	v_mfma_f32_16x16x32_bf16 v[80:83], v[168:171], v[216:219], v[80:83]
	v_mfma_f32_16x16x32_bf16 v[72:75], v[192:195], v[216:219], v[72:75]
	v_mfma_f32_16x16x32_bf16 v[68:71], v[168:171], v[224:227], v[68:71]
	v_mfma_f32_16x16x32_bf16 v[64:67], v[192:195], v[224:227], v[64:67]
	s_barrier
; #define PG8_STAGE(bufoff, gbase, voff) do { _Pragma("unroll") for (int _i = 0; _i < 2; ++_i) \
;         __builtin_amdgcn_global_load_lds((const unsigned*)((const char*)(gbase) + (voff)[_i]), (PG8_LAS unsigned*)(lds + (bufoff) + ldsw + _i * 8192), 16, 0, 0); } while (0)
; #define PG8_LDA(dst, b, h) do { _Pragma("unroll") for (int m = 0; m < 4; ++m) _Pragma("unroll") for (int k = 0; k < 2; ++k) dst[m][k] = *(const PG8_LAS bf16x8*)(lds + PG8_SA(b, h) + aoff + m * 2048 + k * 1024); } while (0)
; #define PG8_MMA(ai, bj, At, Bt) do { __builtin_amdgcn_s_setprio(1); _Pragma("unroll") for (int m = 0; m < 4; ++m) _Pragma("unroll") for (int n = 0; n < 2; ++n) _Pragma("unroll") for (int k = 0; k < 2; ++k) \
;         acc[ai][bj][m][n] = __builtin_amdgcn_mfma_f32_16x16x32_bf16(Bt[n][k], At[m][k], acc[ai][bj][m][n], 0, 0, 0); __builtin_amdgcn_s_setprio(0); } while (0)
; #define PG8_WAIT_V(n) asm volatile("s_waitcnt vmcnt(" #n ")" ::: "memory")
; #define PG8_WAIT_L(n) asm volatile("s_waitcnt lgkmcnt(" #n ")" ::: "memory")
; #define PG8_BAR __builtin_amdgcn_s_barrier()
; #define PG8_SCHED __builtin_amdgcn_sched_barrier(0)
; template <class Epi, class Sched, bool ALIGN_EPI = false, bool SP2 = false>
; __device__ __forceinline__ void gemm_phase(PG8_LAS unsigned char* lds, const Gemm g, const Sched& S, const Epi& E) {
;     ...
;             PG8_LDA(At, 1, 1); PG8_STAGE(PG8_SB(1, 0), b3, voffB); PG8_STAGE(PG8_SB(1, 1), b3 + hstep, voffB); PG8_STAGE(PG8_SA(1, 0), a3, voffA);
;             PG8_WAIT_V(8); PG8_WAIT_L(0); PG8_BAR; PG8_MMA(1, 0, At, B0); PG8_MMA(1, 1, At, B1); PG8_BAR; PG8_SCHED;
	s_setprio 0
	s_add_i32 s69, s93, s0
	v_lshl_add_u64 v[150:151], v[150:151], 0, s[18:19]
	s_mov_b32 m0, s69
	ds_read_b128 v[196:199], v141 offset:49152
	ds_read_b128 v[200:203], v141 offset:50176
	ds_read_b128 v[204:207], v141 offset:51200
	ds_read_b128 v[208:211], v141 offset:52224
	ds_read_b128 v[212:215], v141 offset:53248
	ds_read_b128 v[216:219], v141 offset:54272
	ds_read_b128 v[220:223], v141 offset:55296
	ds_read_b128 v[224:227], v141 offset:56320
	global_load_lds_dwordx4 v[150:151], off
	s_add_i32 m0, s69, 0x2000
	s_add_u32 s74, s74, 0x80080
	v_lshl_add_u64 v[150:151], v[182:183], 0, s[18:19]
	s_addc_u32 s75, s75, 0
	s_add_i32 s68, s68, s0
	global_load_lds_dwordx4 v[150:151], off
	v_lshl_add_u64 v[150:151], s[74:75], 0, v[152:153]
	s_mov_b32 m0, s68
	s_nop 0
	global_load_lds_dwordx4 v[150:151], off
	v_lshl_add_u64 v[150:151], s[74:75], 0, v[132:133]
	s_add_i32 m0, s68, 0x2000
	s_nop 0
	global_load_lds_dwordx4 v[150:151], off
	v_lshl_add_u64 v[150:151], v[184:185], 0, s[18:19]
	s_mov_b32 m0, s26
	s_nop 0
	global_load_lds_dwordx4 v[150:151], off
	v_lshl_add_u64 v[150:151], v[188:189], 0, s[18:19]
	s_mov_b32 m0, s34
	s_nop 0
	global_load_lds_dwordx4 v[150:151], off
	s_waitcnt vmcnt(8)
	s_waitcnt lgkmcnt(0)
	s_setprio 1
	s_barrier
	v_mfma_f32_16x16x32_bf16 v[60:63], v[142:145], v[196:199], v[60:63]
	v_mfma_f32_16x16x32_bf16 v[56:59], v[156:159], v[196:199], v[56:59]
	v_mfma_f32_16x16x32_bf16 v[52:55], v[142:145], v[204:207], v[52:55]
	v_mfma_f32_16x16x32_bf16 v[44:47], v[156:159], v[204:207], v[44:47]
	v_mfma_f32_16x16x32_bf16 v[36:39], v[142:145], v[212:215], v[36:39]
	v_mfma_f32_16x16x32_bf16 v[28:31], v[156:159], v[212:215], v[28:31]
	v_mfma_f32_16x16x32_bf16 v[20:23], v[142:145], v[220:223], v[20:23]
	v_mfma_f32_16x16x32_bf16 v[12:15], v[156:159], v[220:223], v[12:15]
	v_mfma_f32_16x16x32_bf16 v[60:63], v[146:149], v[200:203], v[60:63]
	v_mfma_f32_16x16x32_bf16 v[56:59], v[160:163], v[200:203], v[56:59]
	v_mfma_f32_16x16x32_bf16 v[52:55], v[146:149], v[208:211], v[52:55]
	v_mfma_f32_16x16x32_bf16 v[44:47], v[160:163], v[208:211], v[44:47]
	v_mfma_f32_16x16x32_bf16 v[36:39], v[146:149], v[216:219], v[36:39]
	v_mfma_f32_16x16x32_bf16 v[28:31], v[160:163], v[216:219], v[28:31]
	v_mfma_f32_16x16x32_bf16 v[20:23], v[146:149], v[224:227], v[20:23]
	v_mfma_f32_16x16x32_bf16 v[12:15], v[160:163], v[224:227], v[12:15]
	v_mfma_f32_16x16x32_bf16 v[48:51], v[164:167], v[196:199], v[48:51]
	v_mfma_f32_16x16x32_bf16 v[40:43], v[172:175], v[196:199], v[40:43]
	v_mfma_f32_16x16x32_bf16 v[32:35], v[164:167], v[204:207], v[32:35]
	v_mfma_f32_16x16x32_bf16 v[24:27], v[172:175], v[204:207], v[24:27]
	v_mfma_f32_16x16x32_bf16 v[16:19], v[164:167], v[212:215], v[16:19]
	v_mfma_f32_16x16x32_bf16 v[8:11], v[172:175], v[212:215], v[8:11]
	v_mfma_f32_16x16x32_bf16 v[4:7], v[164:167], v[220:223], v[4:7]
	v_mfma_f32_16x16x32_bf16 v[0:3], v[172:175], v[220:223], v[0:3]
	v_mfma_f32_16x16x32_bf16 v[48:51], v[168:171], v[200:203], v[48:51]
	v_mfma_f32_16x16x32_bf16 v[40:43], v[192:195], v[200:203], v[40:43]
	v_mfma_f32_16x16x32_bf16 v[32:35], v[168:171], v[208:211], v[32:35]
	v_mfma_f32_16x16x32_bf16 v[24:27], v[192:195], v[208:211], v[24:27]
	v_mfma_f32_16x16x32_bf16 v[16:19], v[168:171], v[216:219], v[16:19]
	v_mfma_f32_16x16x32_bf16 v[8:11], v[192:195], v[216:219], v[8:11]
	v_mfma_f32_16x16x32_bf16 v[4:7], v[168:171], v[224:227], v[4:7]
	v_mfma_f32_16x16x32_bf16 v[0:3], v[192:195], v[224:227], v[0:3]
	s_add_i32 s71, s71, 2
	s_add_u32 s48, s48, 0x100
	s_addc_u32 s49, s49, 0
	s_add_u32 s59, s59, 0x100
	s_addc_u32 s63, s63, 0
	s_cmp_gt_u32 s71, 29
	s_cbranch_scc1 .Llastbar_354
	s_barrier
	s_setprio 0
	s_branch .LBB0_354
